# sc1 (no L2 retain) on the 16-byte output-tile stores of gemm_in and gemm_lat epilogues so streamed outputs stop evicting reused panels
# baseline (speedup 1.0000x reference)
; #define WAIT_V0() asm volatile("s_waitcnt vmcnt(0)" ::: "memory")
; DI void gemm_core(char* smem, int nk, const char* Ab, const char* Bb, const unsigned (&aoff)[4], const unsigned (&boff)[4],
;                   f32x16 (&acc)[2][2]) {
;     ...
;   for (int kt = 0; kt < nk; ++kt) {
;     const int cur = kt & 1;
;     if (kt + 1 < nk) stage(cur ^ 1, kt + 1);
;     const char* sb = smem + cur * STAGE_B;
; #pragma unroll
;     for (int ks = 0; ks < 4; ++ks) {
;       bf16x8 af[2], bfr[2];
; #pragma unroll
;       for (int mb = 0; mb < 2; ++mb) af[mb] = *(const bf16x8*)(sb + a_base + mb * 4096 + xo[ks]);
; #pragma unroll
;       for (int nb = 0; nb < 2; ++nb) bfr[nb] = *(const bf16x8*)(sb + b_base + nb * 4096 + xo[ks]);
; #pragma unroll
;       for (int mb = 0; mb < 2; ++mb)
; #pragma unroll
;         for (int nb = 0; nb < 2; ++nb)
;           acc[mb][nb] = __builtin_amdgcn_mfma_f32_32x32x16_bf16(af[mb], bfr[nb], acc[mb][nb], 0, 0, 0);
;     }
;     WAIT_V0();
;     __syncthreads();
;   }
; DI void phase_gemm_lat(const Params& P, int layer, char* smem) {
;     ...
;     gemm_tile(smem, isq ? 6 : 4, Z + (isq ? C_CQ : C_CKV), ZLD, m0, wl + (isq ? WO_UQ : WO_UKV), isq ? 384 : 256, n0, acc);
;     unsigned short* dst = isq ? QB : KV;
;     const int ldd = isq ? 768 : 1024;
.LBB0_414:
	s_and_b32 s22, s21, 0x8000
	s_xor_b32 s23, s22, 0x8000
	v_add_u32_e32 v87, s23, v86
	v_add_u32_e32 v90, 0x4000, v87
	v_readfirstlane_b32 s23, v87
	v_lshl_add_u64 v[88:89], v[64:65], 0, s[12:13]
	s_mov_b32 m0, s23
	v_readfirstlane_b32 s23, v90
	v_add_u32_e32 v90, 0x400, v87
	global_load_lds_dwordx4 v[88:89], off
	v_lshl_add_u64 v[88:89], v[72:73], 0, s[12:13]
	s_mov_b32 m0, s23
	v_readfirstlane_b32 s23, v90
	v_add_u32_e32 v90, 0x4400, v87
	global_load_lds_dwordx4 v[88:89], off
	v_lshl_add_u64 v[88:89], v[66:67], 0, s[12:13]
	s_mov_b32 m0, s23
	v_readfirstlane_b32 s23, v90
	v_add_u32_e32 v90, 0x800, v87
	global_load_lds_dwordx4 v[88:89], off
	v_lshl_add_u64 v[88:89], v[74:75], 0, s[12:13]
	s_mov_b32 m0, s23
	v_readfirstlane_b32 s23, v90
	v_add_u32_e32 v90, 0x4800, v87
	global_load_lds_dwordx4 v[88:89], off
	v_lshl_add_u64 v[88:89], v[68:69], 0, s[12:13]
	s_mov_b32 m0, s23
	v_readfirstlane_b32 s23, v90
	v_add_u32_e32 v90, 0xc00, v87
	global_load_lds_dwordx4 v[88:89], off
	v_lshl_add_u64 v[88:89], v[76:77], 0, s[12:13]
	s_mov_b32 m0, s23
	v_readfirstlane_b32 s23, v90
	v_add_u32_e32 v87, 0x4c00, v87
	global_load_lds_dwordx4 v[88:89], off
	v_lshl_add_u64 v[88:89], v[70:71], 0, s[12:13]
	s_mov_b32 m0, s23
	v_readfirstlane_b32 s23, v87
	global_load_lds_dwordx4 v[88:89], off
	v_lshl_add_u64 v[88:89], v[78:79], 0, s[12:13]
	s_mov_b32 m0, s23
	v_add_u32_e32 v87, s22, v84
	global_load_lds_dwordx4 v[88:89], off
	v_or_b32_e32 v104, s22, v85
	v_add_u32_e32 v92, v87, v83
	v_add_u32_e32 v100, v104, v83
	ds_read_b128 v[88:91], v92
	ds_read_b128 v[92:95], v92 offset:4096
	ds_read_b128 v[96:99], v100 offset:16384
	ds_read_b128 v[100:103], v100 offset:20480
	s_waitcnt lgkmcnt(0)
	v_mfma_f32_32x32x16_bf16 v[48:63], v[88:91], v[96:99], v[48:63]
	s_add_u32 s12, s12, 0x80
	s_addc_u32 s13, s13, 0
	s_add_i32 s21, s21, 0x8000
	s_cmp_lg_u32 s20, s12
	v_mfma_f32_32x32x16_bf16 v[32:47], v[88:91], v[100:103], v[32:47]
	v_mfma_f32_32x32x16_bf16 v[0:15], v[92:95], v[96:99], v[0:15]
	v_mfma_f32_32x32x16_bf16 v[16:31], v[92:95], v[100:103], v[16:31]
	v_add_u32_e32 v92, v87, v82
	v_add_u32_e32 v100, v104, v82
	ds_read_b128 v[88:91], v92
	ds_read_b128 v[92:95], v92 offset:4096
	ds_read_b128 v[96:99], v100 offset:16384
	ds_read_b128 v[100:103], v100 offset:20480
	s_waitcnt lgkmcnt(0)
	v_mfma_f32_32x32x16_bf16 v[48:63], v[88:91], v[96:99], v[48:63]
	v_mfma_f32_32x32x16_bf16 v[32:47], v[88:91], v[100:103], v[32:47]
	v_mfma_f32_32x32x16_bf16 v[0:15], v[92:95], v[96:99], v[0:15]
	v_mfma_f32_32x32x16_bf16 v[16:31], v[92:95], v[100:103], v[16:31]
	v_add_u32_e32 v92, v87, v81
	v_add_u32_e32 v100, v104, v81
	ds_read_b128 v[88:91], v92
	ds_read_b128 v[92:95], v92 offset:4096
	ds_read_b128 v[96:99], v100 offset:16384
	ds_read_b128 v[100:103], v100 offset:20480
	v_add_u32_e32 v87, v87, v80
	s_waitcnt lgkmcnt(0)
	v_mfma_f32_32x32x16_bf16 v[48:63], v[88:91], v[96:99], v[48:63]
	v_mfma_f32_32x32x16_bf16 v[32:47], v[88:91], v[100:103], v[32:47]
	v_mfma_f32_32x32x16_bf16 v[0:15], v[92:95], v[96:99], v[0:15]
	v_mfma_f32_32x32x16_bf16 v[16:31], v[92:95], v[100:103], v[16:31]
	ds_read_b128 v[88:91], v87
	ds_read_b128 v[92:95], v87 offset:4096
	v_add_u32_e32 v87, v104, v80
	ds_read_b128 v[96:99], v87 offset:16384
	ds_read_b128 v[100:103], v87 offset:20480
	s_waitcnt vmcnt(0)
	s_waitcnt vmcnt(0) lgkmcnt(0)
	s_barrier
	v_mfma_f32_32x32x16_bf16 v[48:63], v[88:91], v[96:99], v[48:63]
	v_mfma_f32_32x32x16_bf16 v[32:47], v[88:91], v[100:103], v[32:47]
	v_mfma_f32_32x32x16_bf16 v[0:15], v[92:95], v[96:99], v[0:15]
	v_mfma_f32_32x32x16_bf16 v[16:31], v[92:95], v[100:103], v[16:31]
	s_cbranch_scc1 .LBB0_414
	s_lshl_b32 s12, s19, 15
	s_add_i32 s12, s12, 0x8000
	s_and_b32 s12, s12, 0x8000
	v_add_u32_e32 v84, s12, v84
	v_or_b32_e32 v85, s12, v85
	v_add_u32_e32 v68, v84, v83
	v_add_u32_e32 v76, v85, v83
	ds_read_b128 v[64:67], v68
	ds_read_b128 v[68:71], v68 offset:4096
	ds_read_b128 v[72:75], v76 offset:16384
	ds_read_b128 v[76:79], v76 offset:20480
	s_waitcnt lgkmcnt(1)
	v_mfma_f32_32x32x16_bf16 v[48:63], v[64:67], v[72:75], v[48:63]
	s_and_b64 s[12:13], s[10:11], exec
	s_mov_b32 s12, 0x15000000
	s_cselect_b32 s12, s12, 0x3f00000
	s_add_u32 s19, s74, s12
	s_addc_u32 s20, s75, 0
	s_and_b64 s[10:11], s[10:11], exec
	s_movk_i32 s10, 0x300
	s_waitcnt lgkmcnt(0)
	v_mfma_f32_32x32x16_bf16 v[32:47], v[64:67], v[76:79], v[32:47]
	s_cselect_b32 s10, s10, 0x400
	v_mfma_f32_32x32x16_bf16 v[0:15], v[68:71], v[72:75], v[0:15]
	v_mfma_f32_32x32x16_bf16 v[16:31], v[68:71], v[76:79], v[16:31]
	v_add_u32_e32 v68, v84, v82
	v_add_u32_e32 v76, v85, v82
	ds_read_b128 v[64:67], v68
	ds_read_b128 v[68:71], v68 offset:4096
	ds_read_b128 v[72:75], v76 offset:16384
	ds_read_b128 v[76:79], v76 offset:20480
	s_waitcnt lgkmcnt(1)
	v_mfma_f32_32x32x16_bf16 v[48:63], v[64:67], v[72:75], v[48:63]
	s_waitcnt lgkmcnt(0)
	v_mfma_f32_32x32x16_bf16 v[32:47], v[64:67], v[76:79], v[32:47]
	v_mfma_f32_32x32x16_bf16 v[0:15], v[68:71], v[72:75], v[0:15]
	v_mfma_f32_32x32x16_bf16 v[16:31], v[68:71], v[76:79], v[16:31]
	v_add_u32_e32 v68, v84, v81
	v_add_u32_e32 v76, v85, v81
	ds_read_b128 v[64:67], v68
	ds_read_b128 v[68:71], v68 offset:4096
	ds_read_b128 v[72:75], v76 offset:16384
	ds_read_b128 v[76:79], v76 offset:20480
	s_waitcnt lgkmcnt(1)
	v_mfma_f32_32x32x16_bf16 v[48:63], v[64:67], v[72:75], v[48:63]
	s_waitcnt lgkmcnt(0)
	v_mfma_f32_32x32x16_bf16 v[32:47], v[64:67], v[76:79], v[32:47]
	v_mfma_f32_32x32x16_bf16 v[0:15], v[68:71], v[72:75], v[0:15]
	v_mfma_f32_32x32x16_bf16 v[16:31], v[68:71], v[76:79], v[16:31]
	v_add_u32_e32 v68, v84, v80
	v_add_u32_e32 v76, v85, v80
	ds_read_b128 v[64:67], v68
	ds_read_b128 v[68:71], v68 offset:4096
	ds_read_b128 v[72:75], v76 offset:16384
	ds_read_b128 v[76:79], v76 offset:20480
	s_waitcnt vmcnt(0)
	s_waitcnt lgkmcnt(0)
	s_barrier
; DI int ltid() { int t = threadIdx.x; asm volatile("" : "+v"(t)); return t; }
; template <class F>
; DI void epi_foreach(const f32x16 (&acc)[2][2], F f) {
;   const int lane = ltid() & 63, w = ltid() >> 6;
;   const int wm = w >> 1, wn = w & 1;
; #pragma unroll
;   for (int mb = 0; mb < 2; ++mb)
; #pragma unroll
;     for (int nb = 0; nb < 2; ++nb)
; #pragma unroll
;       for (int r = 0; r < 16; ++r) {
;         const int row = wm * 64 + mb * 32 + (r & 3) + 8 * (r >> 2) + 4 * (lane >> 5);
;         const int col = wn * 64 + nb * 32 + (lane & 31);
;         f(row, col, acc[mb][nb][r]);
;         if ((r & 7) == 7) __builtin_amdgcn_sched_barrier(0);
;       }
; }
; DI void phase_gemm_lat(const Params& P, int layer, char* smem) {
;     ...
;     epi_foreach(acc, [&](int row, int col, float v) __attribute__((always_inline)) { Cs[row * 136 + col] = f2bf(v); });
;     __syncthreads();
	v_mfma_f32_32x32x16_bf16 v[48:63], v[64:67], v[72:75], v[48:63]
	v_mfma_f32_32x32x16_bf16 v[32:47], v[64:67], v[76:79], v[32:47]
	v_mov_b32_e32 v64, v161
	v_mov_b32_e32 v65, v161
	v_lshrrev_b32_e32 v67, 3, v64
	v_and_b32_e32 v67, 4, v67
	v_lshrrev_b32_e32 v66, 1, v65
	v_and_b32_e32 v64, 31, v64
	v_and_or_b32 v64, v65, 64, v64
	v_and_or_b32 v65, v66, s8, v67
	v_mul_lo_u32 v65, v65, s97
	s_nop 1
	v_cvt_pk_bf16_f32 v48, v48, s0
	v_lshl_add_u32 v64, v64, 1, v65
	ds_write_b16 v64, v48
	v_cvt_pk_bf16_f32 v48, v49, s0
	ds_write_b16 v64, v48 offset:272
	v_cvt_pk_bf16_f32 v48, v50, s0
	ds_write_b16 v64, v48 offset:544
	v_cvt_pk_bf16_f32 v48, v51, s0
	ds_write_b16 v64, v48 offset:816
	v_cvt_pk_bf16_f32 v48, v52, s0
	ds_write_b16 v64, v48 offset:2176
	v_cvt_pk_bf16_f32 v48, v53, s0
	ds_write_b16 v64, v48 offset:2448
	v_cvt_pk_bf16_f32 v48, v54, s0
	ds_write_b16 v64, v48 offset:2720
	v_cvt_pk_bf16_f32 v48, v55, s0
	v_mfma_f32_32x32x16_bf16 v[0:15], v[68:71], v[72:75], v[0:15]
	ds_write_b16 v64, v48 offset:2992
	v_mfma_f32_32x32x16_bf16 v[16:31], v[68:71], v[76:79], v[16:31]
	v_cvt_pk_bf16_f32 v48, v56, s0
	ds_write_b16 v64, v48 offset:4352
	v_cvt_pk_bf16_f32 v48, v57, s0
	ds_write_b16 v64, v48 offset:4624
	v_cvt_pk_bf16_f32 v48, v58, s0
	ds_write_b16 v64, v48 offset:4896
	v_cvt_pk_bf16_f32 v48, v59, s0
	ds_write_b16 v64, v48 offset:5168
	v_cvt_pk_bf16_f32 v48, v60, s0
	ds_write_b16 v64, v48 offset:6528
	v_cvt_pk_bf16_f32 v48, v61, s0
	ds_write_b16 v64, v48 offset:6800
	v_cvt_pk_bf16_f32 v48, v62, s0
	ds_write_b16 v64, v48 offset:7072
	v_cvt_pk_bf16_f32 v48, v63, s0
	ds_write_b16 v64, v48 offset:7344
	v_cvt_pk_bf16_f32 v32, v32, s0
	ds_write_b16 v64, v32 offset:64
	v_cvt_pk_bf16_f32 v32, v33, s0
	ds_write_b16 v64, v32 offset:336
	v_cvt_pk_bf16_f32 v32, v34, s0
	ds_write_b16 v64, v32 offset:608
	v_cvt_pk_bf16_f32 v32, v35, s0
	ds_write_b16 v64, v32 offset:880
	v_cvt_pk_bf16_f32 v32, v36, s0
	ds_write_b16 v64, v32 offset:2240
	v_cvt_pk_bf16_f32 v32, v37, s0
	ds_write_b16 v64, v32 offset:2512
	v_cvt_pk_bf16_f32 v32, v38, s0
	ds_write_b16 v64, v32 offset:2784
	v_cvt_pk_bf16_f32 v32, v39, s0
	ds_write_b16 v64, v32 offset:3056
	v_cvt_pk_bf16_f32 v32, v40, s0
	ds_write_b16 v64, v32 offset:4416
	v_cvt_pk_bf16_f32 v32, v41, s0
	ds_write_b16 v64, v32 offset:4688
	v_cvt_pk_bf16_f32 v32, v42, s0
	ds_write_b16 v64, v32 offset:4960
	v_cvt_pk_bf16_f32 v32, v43, s0
	ds_write_b16 v64, v32 offset:5232
	v_cvt_pk_bf16_f32 v32, v44, s0
	ds_write_b16 v64, v32 offset:6592
	v_cvt_pk_bf16_f32 v32, v45, s0
	ds_write_b16 v64, v32 offset:6864
	v_cvt_pk_bf16_f32 v32, v46, s0
	ds_write_b16 v64, v32 offset:7136
	v_cvt_pk_bf16_f32 v32, v47, s0
	ds_write_b16 v64, v32 offset:7408
	v_cvt_pk_bf16_f32 v0, v0, s0
	ds_write_b16 v64, v0 offset:8704
	v_cvt_pk_bf16_f32 v0, v1, s0
	ds_write_b16 v64, v0 offset:8976
	v_cvt_pk_bf16_f32 v0, v2, s0
	ds_write_b16 v64, v0 offset:9248
	v_cvt_pk_bf16_f32 v0, v3, s0
	ds_write_b16 v64, v0 offset:9520
	v_cvt_pk_bf16_f32 v0, v4, s0
	ds_write_b16 v64, v0 offset:10880
	v_cvt_pk_bf16_f32 v0, v5, s0
	ds_write_b16 v64, v0 offset:11152
	v_cvt_pk_bf16_f32 v0, v6, s0
	ds_write_b16 v64, v0 offset:11424
	v_cvt_pk_bf16_f32 v0, v7, s0
	ds_write_b16 v64, v0 offset:11696
	v_cvt_pk_bf16_f32 v0, v8, s0
	ds_write_b16 v64, v0 offset:13056
	v_cvt_pk_bf16_f32 v0, v9, s0
	ds_write_b16 v64, v0 offset:13328
	v_cvt_pk_bf16_f32 v0, v10, s0
	ds_write_b16 v64, v0 offset:13600
	v_cvt_pk_bf16_f32 v0, v11, s0
	ds_write_b16 v64, v0 offset:13872
	v_cvt_pk_bf16_f32 v0, v12, s0
	ds_write_b16 v64, v0 offset:15232
	v_cvt_pk_bf16_f32 v0, v13, s0
	ds_write_b16 v64, v0 offset:15504
	v_cvt_pk_bf16_f32 v0, v14, s0
	ds_write_b16 v64, v0 offset:15776
	v_cvt_pk_bf16_f32 v0, v15, s0
	ds_write_b16 v64, v0 offset:16048
	v_cvt_pk_bf16_f32 v0, v16, s0
	ds_write_b16 v64, v0 offset:8768
	v_cvt_pk_bf16_f32 v0, v17, s0
	ds_write_b16 v64, v0 offset:9040
	v_cvt_pk_bf16_f32 v0, v18, s0
	ds_write_b16 v64, v0 offset:9312
	v_cvt_pk_bf16_f32 v0, v19, s0
	ds_write_b16 v64, v0 offset:9584
	v_cvt_pk_bf16_f32 v0, v20, s0
	ds_write_b16 v64, v0 offset:10944
	v_cvt_pk_bf16_f32 v0, v21, s0
	ds_write_b16 v64, v0 offset:11216
	v_cvt_pk_bf16_f32 v0, v22, s0
	ds_write_b16 v64, v0 offset:11488
	v_cvt_pk_bf16_f32 v0, v23, s0
	ds_write_b16 v64, v0 offset:11760
	v_cvt_pk_bf16_f32 v0, v24, s0
	ds_write_b16 v64, v0 offset:13120
	v_cvt_pk_bf16_f32 v0, v25, s0
	ds_write_b16 v64, v0 offset:13392
	v_cvt_pk_bf16_f32 v0, v26, s0
	ds_write_b16 v64, v0 offset:13664
	v_cvt_pk_bf16_f32 v0, v27, s0
	ds_write_b16 v64, v0 offset:13936
	v_cvt_pk_bf16_f32 v0, v28, s0
	ds_write_b16 v64, v0 offset:15296
	v_cvt_pk_bf16_f32 v0, v29, s0
	ds_write_b16 v64, v0 offset:15568
	v_cvt_pk_bf16_f32 v0, v30, s0
	ds_write_b16 v64, v0 offset:15840
	v_cvt_pk_bf16_f32 v0, v31, s0
	ds_write_b16 v64, v0 offset:16112
	s_mul_hi_i32 s13, s10, s18
	s_mul_i32 s12, s10, s18
	s_lshl_b64 s[12:13], s[12:13], 1
	s_add_u32 s11, s19, s12
	s_addc_u32 s12, s20, s13
	s_lshl_b64 s[0:1], s[0:1], 1
	v_mov_b32_e32 v8, v161
	s_waitcnt lgkmcnt(0)
	s_barrier
; DI int ltid() { int t = threadIdx.x; asm volatile("" : "+v"(t)); return t; }
; DI void store_tile16(const unsigned short* Cs, unsigned short* dst, int ldd) {
;   const int tid = ltid();
; #pragma unroll
;   for (int i = 0; i < 8; ++i) {
;     const int idx = tid + 256 * i;
;     const int row = idx >> 4, c8 = (idx & 15) * 8;
;     *(u32x4*)(dst + (size_t)row * ldd + c8) = *(const u32x4*)(Cs + row * 136 + c8);
;   }
; }
; DI void phase_gemm_lat(const Params& P, int layer, char* smem) {
;     ...
;     store_tile16(Cs, dst + (size_t)m0 * ldd + n0, ldd);
;     __syncthreads();
;   }
	s_add_u32 s0, s11, s0
	s_addc_u32 s1, s12, s1
	v_lshlrev_b32_e32 v0, 4, v8
	v_and_b32_e32 v136, 0xf0, v0
	v_ashrrev_i32_e32 v6, 4, v8
	v_lshl_add_u64 v[4:5], s[0:1], 0, v[136:137]
	v_mad_u64_u32 v[0:1], s[0:1], v6, s97, v[136:137]
	ds_read_b128 v[0:3], v0
	v_mad_i64_i32 v[6:7], s[0:1], s10, v6, 0
	v_lshl_add_u64 v[6:7], v[6:7], 1, v[4:5]
	s_add_i32 s17, s17, s70
	s_waitcnt lgkmcnt(0)
	global_store_dwordx4 v[6:7], v[0:3], off sc1
	s_cmpk_gt_i32 s17, 0xdff
	s_nop 0
	v_add_u32_e32 v0, 0x100, v8
	v_ashrrev_i32_e32 v6, 4, v0
	v_mad_u64_u32 v[0:1], s[0:1], v6, s97, v[136:137]
	ds_read_b128 v[0:3], v0
	v_mad_i64_i32 v[6:7], s[0:1], s10, v6, 0
	v_lshl_add_u64 v[6:7], v[6:7], 1, v[4:5]
	s_waitcnt lgkmcnt(0)
	global_store_dwordx4 v[6:7], v[0:3], off sc1
	s_nop 1
	v_add_u32_e32 v0, 0x200, v8
	v_ashrrev_i32_e32 v6, 4, v0
	v_mad_u64_u32 v[0:1], s[0:1], v6, s97, v[136:137]
	ds_read_b128 v[0:3], v0
	v_mad_i64_i32 v[6:7], s[0:1], s10, v6, 0
	v_lshl_add_u64 v[6:7], v[6:7], 1, v[4:5]
	s_waitcnt lgkmcnt(0)
	global_store_dwordx4 v[6:7], v[0:3], off sc1
	s_nop 1
	v_add_u32_e32 v0, 0x300, v8
	v_ashrrev_i32_e32 v6, 4, v0
	v_mad_u64_u32 v[0:1], s[0:1], v6, s97, v[136:137]
	ds_read_b128 v[0:3], v0
	v_mad_i64_i32 v[6:7], s[0:1], s10, v6, 0
	v_lshl_add_u64 v[6:7], v[6:7], 1, v[4:5]
	s_waitcnt lgkmcnt(0)
	global_store_dwordx4 v[6:7], v[0:3], off sc1
	s_nop 1
	v_add_u32_e32 v0, 0x400, v8
	v_ashrrev_i32_e32 v6, 4, v0
	v_mad_u64_u32 v[0:1], s[0:1], v6, s97, v[136:137]
	ds_read_b128 v[0:3], v0
	v_mad_i64_i32 v[6:7], s[0:1], s10, v6, 0
	v_lshl_add_u64 v[6:7], v[6:7], 1, v[4:5]
	s_waitcnt lgkmcnt(0)
	global_store_dwordx4 v[6:7], v[0:3], off sc1
	s_nop 1
	v_add_u32_e32 v0, 0x500, v8
	v_ashrrev_i32_e32 v6, 4, v0
	v_mad_u64_u32 v[0:1], s[0:1], v6, s97, v[136:137]
	ds_read_b128 v[0:3], v0
	v_mad_i64_i32 v[6:7], s[0:1], s10, v6, 0
	v_lshl_add_u64 v[6:7], v[6:7], 1, v[4:5]
	s_waitcnt lgkmcnt(0)
	global_store_dwordx4 v[6:7], v[0:3], off sc1
	s_nop 1
	v_add_u32_e32 v0, 0x600, v8
	v_ashrrev_i32_e32 v6, 4, v0
	v_mad_u64_u32 v[0:1], s[0:1], v6, s97, v[136:137]
	ds_read_b128 v[0:3], v0
	v_mad_i64_i32 v[6:7], s[0:1], s10, v6, 0
	v_lshl_add_u64 v[6:7], v[6:7], 1, v[4:5]
	s_waitcnt lgkmcnt(0)
	global_store_dwordx4 v[6:7], v[0:3], off sc1
	s_nop 1
	v_add_u32_e32 v0, 0x700, v8
	v_ashrrev_i32_e32 v6, 4, v0
	v_mad_u64_u32 v[0:1], s[0:1], v6, s97, v[136:137]
	ds_read_b128 v[0:3], v0
	v_mad_i64_i32 v[6:7], s[0:1], s10, v6, 0
	v_lshl_add_u64 v[4:5], v[6:7], 1, v[4:5]
	s_waitcnt lgkmcnt(0)
	global_store_dwordx4 v[4:5], v[0:3], off sc1
	s_barrier
	s_cbranch_scc0 .LBB0_413
	v_readlane_b32 s18, v255, 3
	v_readlane_b32 s19, v255, 4

; #define WAIT_V0() asm volatile("s_waitcnt vmcnt(0)" ::: "memory")
; DI int glds_row(int i) { const int tid = ltid(); return ((tid >> 6) * 4 + i) * 8 + ((tid & 63) >> 3); }
; DI int glds_chunk(int row) { return (ltid() & 7) ^ ((row >> 1) & 7); }
; DI void gemm_core(char* smem, int nk, const char* Ab, const char* Bb, const unsigned (&aoff)[4], const unsigned (&boff)[4],
;                   f32x16 (&acc)[2][2]) {
;     ...
;   auto stage = [&](int buf, int kt) __attribute__((always_inline)) {
;     const char* ak = Ab + kt * 128;
;     const char* bk = Bb + kt * 128;
;     char* sa = smem + buf * STAGE_B + w * 4096;
; #pragma unroll
;     for (int i = 0; i < 4; ++i) {
;       __builtin_amdgcn_global_load_lds((const unsigned*)(ak + aoff[i]), (unsigned*)(sa + i * 1024), 16, 0, 0);
;       __builtin_amdgcn_global_load_lds((const unsigned*)(bk + boff[i]), (unsigned*)(sa + 16384 + i * 1024), 16, 0, 0);
;     }
;   };
;   stage(0, 0);
;   WAIT_V0();
;   __syncthreads();
;   for (int kt = 0; kt < nk; ++kt) {
;     const int cur = kt & 1;
;     if (kt + 1 < nk) stage(cur ^ 1, kt + 1);
; DI void gemm_tile(char* smem, int nk, const bf16* A, int lda, int m0, const bf16* Bt, int ldb, int n0, f32x16 (&acc)[2][2]) {
;   unsigned aoff[4], boff[4];
; #pragma unroll
;   for (int i = 0; i < 4; ++i) {
;     const int row = glds_row(i), ch = glds_chunk(row);
;     aoff[i] = (unsigned)((row * lda + ch * 8) * 2);
;     boff[i] = (unsigned)((row * ldb + ch * 8) * 2);
;   }
;   gemm_core(smem, nk, (const char*)(A + (size_t)m0 * lda), (const char*)(Bt + (size_t)n0 * ldb), aoff, boff, acc);
; }
.LBB0_436:
	v_mov_b32_e32 v0, v161
	s_ashr_i32 s0, s14, 3
	v_lshrrev_b32_e32 v1, 1, v0
	v_lshrrev_b32_e32 v2, 3, v0
	v_bfe_u32 v0, v0, 3, 3
	v_and_or_b32 v0, v1, s9, v0
	v_mov_b32_e32 v1, v161
	v_bfe_u32 v2, v2, 1, 2
	v_xor_b32_e32 v1, v2, v1
	v_lshlrev_b32_e32 v0, 11, v0
	v_lshlrev_b32_e32 v1, 4, v1
	v_and_or_b32 v136, v1, s92, v0
	v_mov_b32_e32 v0, v161
	s_and_b32 s1, s0, 0xffffffc0
	v_ashrrev_i32_e32 v1, 1, v0
	v_and_b32_e32 v1, 0xffffffe0, v1
	v_bfe_u32 v0, v0, 3, 3
	v_or3_b32 v0, v0, v1, 8
	v_mov_b32_e32 v1, v161
	v_lshrrev_b32_e32 v2, 1, v0
	v_xor_b32_e32 v1, v2, v1
	v_lshlrev_b32_e32 v0, 11, v0
	v_lshlrev_b32_e32 v1, 4, v1
	v_and_or_b32 v0, v1, s92, v0
	v_mov_b32_e32 v1, v161
	s_lshl_b32 s10, s0, 1
	v_lshrrev_b32_e32 v2, 1, v1
	v_lshrrev_b32_e32 v3, 3, v1
	v_bfe_u32 v1, v1, 3, 3
	v_and_or_b32 v1, v2, s9, v1
	v_mov_b32_e32 v2, v161
	s_bfe_u32 s11, s0, 0x10005
	v_bfe_u32 v3, v3, 1, 2
	s_and_b32 s10, s10, 62
	s_or_b32 s1, s11, s1
	v_xor_b32_e32 v2, v3, v2
	s_or_b32 s1, s1, s10
	s_or_b32 s10, s0, 63
	v_lshlrev_b32_e32 v2, 4, v2
	s_cmpk_lt_i32 s10, 0x2c0
	v_lshlrev_b32_e32 v1, 11, v1
	v_and_b32_e32 v2, 0x70, v2
	s_cselect_b32 s1, s1, s0
	v_or3_b32 v2, v1, v2, s8
	v_mov_b32_e32 v1, v161
	s_mul_hi_i32 s10, s1, 0x2e8ba2e9
	s_lshr_b32 s11, s10, 31
	v_ashrrev_i32_e32 v3, 1, v1
	s_ashr_i32 s10, s10, 1
	v_and_b32_e32 v3, 0xffffffe0, v3
	v_bfe_u32 v1, v1, 3, 3
	s_and_b32 s0, s13, 0xc0
	s_add_i32 s10, s10, s11
	v_or3_b32 v1, v1, v3, 24
	v_mov_b32_e32 v3, v161
	s_add_i32 s15, s10, s0
	s_bfe_i32 s11, s14, 0x10002
	s_mul_i32 s10, s10, 11
	v_lshrrev_b32_e32 v4, 1, v1
	s_and_b32 s11, s11, 11
	s_sub_i32 s1, s1, s10
	v_xor_b32_e32 v3, v4, v3
	s_lshl_b32 s0, s15, 7
	s_add_i32 s1, s1, s11
	v_lshlrev_b32_e32 v1, 11, v1
	v_lshlrev_b32_e32 v3, 4, v3
	v_mov_b32_e32 v12, v161
	s_lshl_b32 s10, s1, 7
	v_and_or_b32 v4, v3, s92, v1
	s_ashr_i32 s1, s0, 31
	s_lshl_b64 s[16:17], s[0:1], 11
	v_and_b32_e32 v1, 31, v12
	v_lshrrev_b32_e32 v5, 1, v12
	v_and_or_b32 v1, v5, s6, v1
	s_add_u32 s16, s84, s16
	v_lshlrev_b32_e32 v112, 7, v1
	v_lshlrev_b32_e32 v1, 6, v12
	s_addc_u32 s17, s85, s17
	s_ashr_i32 s11, s10, 31
	v_and_b32_e32 v89, 0xfffff000, v1
	s_lshl_b64 s[18:19], s[10:11], 11
	v_add_u32_e32 v88, 0x4000, v89
	v_readfirstlane_b32 s20, v89
	s_add_u32 s18, s2, s18
	s_mov_b32 m0, s20
	v_readfirstlane_b32 s21, v88
	v_or_b32_e32 v90, 0x400, v89
	s_addc_u32 s19, s12, s19
	global_load_lds_dwordx4 v136, s[16:17]
	s_mov_b32 m0, s21
	v_readfirstlane_b32 s22, v90
	v_add_u32_e32 v91, 0x4400, v89
	global_load_lds_dwordx4 v136, s[18:19]
	s_mov_b32 m0, s22
	v_readfirstlane_b32 s23, v91
	v_or_b32_e32 v92, 0x800, v89
	global_load_lds_dwordx4 v0, s[16:17]
	s_mov_b32 m0, s23
	v_readfirstlane_b32 s28, v92
	v_add_u32_e32 v93, 0x4800, v89
	global_load_lds_dwordx4 v0, s[18:19]
	s_mov_b32 m0, s28
	v_readfirstlane_b32 s29, v93
	v_or_b32_e32 v94, 0xc00, v89
	global_load_lds_dwordx4 v2, s[16:17]
	s_mov_b32 m0, s29
	v_readfirstlane_b32 s40, v94
	v_add_u32_e32 v95, 0x4c00, v89
	v_lshrrev_b32_e32 v3, 5, v12
	v_bfe_u32 v99, v12, 1, 3
	global_load_lds_dwordx4 v2, s[18:19]
	s_mov_b32 m0, s40
	v_readfirstlane_b32 s41, v95
	v_add_u32_e32 v97, 0x8000, v89
	v_bitop3_b32 v3, v3, v99, 1 bitop3:0x6c
	v_lshl_add_u64 v[64:65], s[16:17], 0, v[136:137]
	v_mov_b32_e32 v1, v137
	global_load_lds_dwordx4 v4, s[16:17]
	s_mov_b32 m0, s41
	v_add_u32_e32 v96, 0xc000, v89
	v_readfirstlane_b32 s42, v97
	v_lshlrev_b32_e32 v6, 4, v3
	v_lshl_add_u64 v[66:67], s[18:19], 0, v[136:137]
	v_lshl_add_u64 v[68:69], s[16:17], 0, v[0:1]
	v_lshl_add_u64 v[70:71], s[18:19], 0, v[0:1]
	v_mov_b32_e32 v3, v137
	global_load_lds_dwordx4 v4, s[18:19]
	v_lshl_add_u64 v[0:1], v[64:65], 0, s[94:95]
	s_mov_b32 m0, s42
	v_readfirstlane_b32 s43, v96
	v_add_u32_e32 v98, 0x8400, v89
	v_lshl_add_u64 v[72:73], s[16:17], 0, v[2:3]
	v_lshl_add_u64 v[74:75], s[18:19], 0, v[2:3]
	global_load_lds_dwordx4 v[0:1], off
	v_lshl_add_u64 v[0:1], v[66:67], 0, s[94:95]
	s_mov_b32 m0, s43
	v_readfirstlane_b32 s44, v98
	v_add_u32_e32 v2, 0xc400, v89
	v_mov_b32_e32 v5, v137
	global_load_lds_dwordx4 v[0:1], off
	v_lshl_add_u64 v[0:1], v[68:69], 0, s[94:95]
	s_mov_b32 m0, s44
	v_readfirstlane_b32 s1, v2
	v_add_u32_e32 v2, 0x8800, v89
	v_lshl_add_u64 v[76:77], s[16:17], 0, v[4:5]
	global_load_lds_dwordx4 v[0:1], off
	v_lshl_add_u64 v[0:1], v[70:71], 0, s[94:95]
	s_mov_b32 m0, s1
	v_readfirstlane_b32 s16, v2
	v_add_u32_e32 v2, 0xc800, v89
	global_load_lds_dwordx4 v[0:1], off
	v_lshl_add_u64 v[0:1], v[72:73], 0, s[94:95]
	s_mov_b32 m0, s16
	v_readfirstlane_b32 s17, v2
	v_add_u32_e32 v2, 0x8c00, v89
	v_lshl_add_u64 v[78:79], s[18:19], 0, v[4:5]
	global_load_lds_dwordx4 v[0:1], off
	v_lshl_add_u64 v[0:1], v[74:75], 0, s[94:95]
	s_mov_b32 m0, s17
	v_readfirstlane_b32 s18, v2
	v_add_u32_e32 v2, 0xcc00, v89
	global_load_lds_dwordx4 v[0:1], off
	v_lshl_add_u64 v[0:1], v[76:77], 0, s[94:95]
	s_mov_b32 m0, s18
	v_readfirstlane_b32 s19, v2
	global_load_lds_dwordx4 v[0:1], off
	v_lshl_add_u64 v[0:1], v[78:79], 0, s[94:95]
	s_mov_b32 m0, s19
	v_or_b32_e32 v80, v112, v6
	global_load_lds_dwordx4 v[0:1], off
	s_waitcnt vmcnt(8)
	s_waitcnt vmcnt(8) lgkmcnt(0)
	s_barrier
; #define WAIT_V0() asm volatile("s_waitcnt vmcnt(0)" ::: "memory")
; DI void gemm_core(char* smem, int nk, const char* Ab, const char* Bb, const unsigned (&aoff)[4], const unsigned (&boff)[4],
;                   f32x16 (&acc)[2][2]) {
;     ...
;   stage(0, 0);
;   WAIT_V0();
;   __syncthreads();
;   for (int kt = 0; kt < nk; ++kt) {
;     const int cur = kt & 1;
;     if (kt + 1 < nk) stage(cur ^ 1, kt + 1);
;     const char* sb = smem + cur * STAGE_B;
; #pragma unroll
;     for (int ks = 0; ks < 4; ++ks) {
;       bf16x8 af[2], bfr[2];
; #pragma unroll
;       for (int mb = 0; mb < 2; ++mb) af[mb] = *(const bf16x8*)(sb + a_base + mb * 4096 + xo[ks]);
; #pragma unroll
;       for (int nb = 0; nb < 2; ++nb) bfr[nb] = *(const bf16x8*)(sb + b_base + nb * 4096 + xo[ks]);
; #pragma unroll
;       for (int mb = 0; mb < 2; ++mb)
; #pragma unroll
;         for (int nb = 0; nb < 2; ++nb)
;           acc[mb][nb] = __builtin_amdgcn_mfma_f32_32x32x16_bf16(af[mb], bfr[nb], acc[mb][nb], 0, 0, 0);
;     }
;     WAIT_V0();
;     __syncthreads();
;   }
	ds_read_b128 v[0:3], v80
	v_lshlrev_b32_e32 v4, 7, v12
	v_and_b32_e32 v113, 0x2f80, v4
	v_or_b32_e32 v82, v113, v6
	ds_read_b128 v[4:7], v82 offset:16384
	ds_read_b128 v[8:11], v82 offset:20480
	s_waitcnt lgkmcnt(0)
	v_mfma_f32_32x32x16_bf16 v[48:63], v[0:3], v[4:7], 0
	v_bfe_u32 v114, v12, 5, 1
	s_mov_b32 m0, s20
	v_mfma_f32_32x32x16_bf16 v[32:47], v[0:3], v[8:11], 0
	ds_read_b128 v[0:3], v80 offset:4096
	s_waitcnt lgkmcnt(0)
	v_mfma_f32_32x32x16_bf16 v[16:31], v[0:3], v[4:7], 0
	v_bitop3_b32 v4, v114, v99, 2 bitop3:0x36
	v_lshlrev_b32_e32 v83, 4, v4
	v_or_b32_e32 v81, v112, v83
	ds_read_b128 v[84:87], v81
	v_or_b32_e32 v83, v113, v83
	ds_read_b128 v[100:103], v83 offset:16384
	ds_read_b128 v[104:107], v83 offset:20480
	s_waitcnt lgkmcnt(0)
	v_mfma_f32_32x32x16_bf16 v[48:63], v[84:87], v[100:103], v[48:63]
	v_mfma_f32_32x32x16_bf16 v[32:47], v[84:87], v[104:107], v[32:47]
	ds_read_b128 v[84:87], v81 offset:4096
	v_mfma_f32_32x32x16_bf16 v[0:15], v[0:3], v[8:11], 0
	s_waitcnt lgkmcnt(0)
	v_mfma_f32_32x32x16_bf16 v[16:31], v[84:87], v[100:103], v[16:31]
	v_bitop3_b32 v100, v114, v99, 4 bitop3:0x36
	v_lshlrev_b32_e32 v108, 4, v100
	v_mfma_f32_32x32x16_bf16 v[0:15], v[84:87], v[104:107], v[0:15]
	v_or_b32_e32 v84, v112, v108
	ds_read_b128 v[100:103], v84
	v_or_b32_e32 v85, v113, v108
	ds_read_b128 v[104:107], v85 offset:16384
	ds_read_b128 v[108:111], v85 offset:20480
	v_bitop3_b32 v86, v114, v99, 6 bitop3:0x36
	v_lshlrev_b32_e32 v87, 4, v86
	s_waitcnt lgkmcnt(0)
	v_mfma_f32_32x32x16_bf16 v[48:63], v[100:103], v[104:107], v[48:63]
	v_or_b32_e32 v86, v112, v87
	v_or_b32_e32 v87, v113, v87
	v_mfma_f32_32x32x16_bf16 v[32:47], v[100:103], v[108:111], v[32:47]
	ds_read_b128 v[100:103], v84 offset:4096
	s_waitcnt lgkmcnt(0)
	v_mfma_f32_32x32x16_bf16 v[16:31], v[100:103], v[104:107], v[16:31]
	ds_read_b128 v[104:107], v87 offset:16384
	v_mfma_f32_32x32x16_bf16 v[0:15], v[100:103], v[108:111], v[0:15]
	ds_read_b128 v[100:103], v86
	ds_read_b128 v[108:111], v87 offset:20480
	s_waitcnt lgkmcnt(0)
	v_mfma_f32_32x32x16_bf16 v[48:63], v[100:103], v[104:107], v[48:63]
	v_mfma_f32_32x32x16_bf16 v[32:47], v[100:103], v[108:111], v[32:47]
	ds_read_b128 v[100:103], v86 offset:4096
	s_waitcnt vmcnt(0)
	s_waitcnt vmcnt(0) lgkmcnt(0)
	s_barrier
	v_mfma_f32_32x32x16_bf16 v[16:31], v[100:103], v[104:107], v[16:31]
	v_mfma_f32_32x32x16_bf16 v[0:15], v[100:103], v[108:111], v[0:15]
	v_lshl_add_u64 v[100:101], v[64:65], 0, s[36:37]
	global_load_lds_dwordx4 v[100:101], off
	v_lshl_add_u64 v[100:101], v[66:67], 0, s[36:37]
	s_mov_b32 m0, s21
	s_nop 0
	global_load_lds_dwordx4 v[100:101], off
	v_lshl_add_u64 v[100:101], v[68:69], 0, s[36:37]
	s_mov_b32 m0, s22
	s_nop 0
	global_load_lds_dwordx4 v[100:101], off
	v_lshl_add_u64 v[100:101], v[70:71], 0, s[36:37]
	s_mov_b32 m0, s23
	s_nop 0
	global_load_lds_dwordx4 v[100:101], off
	v_lshl_add_u64 v[100:101], v[72:73], 0, s[36:37]
	s_mov_b32 m0, s28
	s_nop 0
	global_load_lds_dwordx4 v[100:101], off
	v_lshl_add_u64 v[100:101], v[74:75], 0, s[36:37]
	s_mov_b32 m0, s29
	s_nop 0
	global_load_lds_dwordx4 v[100:101], off
	v_lshl_add_u64 v[100:101], v[76:77], 0, s[36:37]
	s_mov_b32 m0, s40
	s_nop 0
	global_load_lds_dwordx4 v[100:101], off
	v_lshl_add_u64 v[100:101], v[78:79], 0, s[36:37]
	s_mov_b32 m0, s41
	s_nop 0
	global_load_lds_dwordx4 v[100:101], off
	ds_read_b128 v[100:103], v80 offset:32768
	ds_read_b128 v[104:107], v82 offset:49152
	ds_read_b128 v[108:111], v82 offset:53248
	s_waitcnt lgkmcnt(0)
	v_mfma_f32_32x32x16_bf16 v[48:63], v[100:103], v[104:107], v[48:63]
	s_mov_b32 m0, s42
	v_mfma_f32_32x32x16_bf16 v[32:47], v[100:103], v[108:111], v[32:47]
	ds_read_b128 v[100:103], v80 offset:36864
	s_waitcnt lgkmcnt(0)
	v_mfma_f32_32x32x16_bf16 v[16:31], v[100:103], v[104:107], v[16:31]
	v_mfma_f32_32x32x16_bf16 v[0:15], v[100:103], v[108:111], v[0:15]
	ds_read_b128 v[100:103], v81 offset:32768
	ds_read_b128 v[104:107], v83 offset:49152
	ds_read_b128 v[108:111], v83 offset:53248
	s_waitcnt lgkmcnt(0)
	v_mfma_f32_32x32x16_bf16 v[48:63], v[100:103], v[104:107], v[48:63]
	v_mfma_f32_32x32x16_bf16 v[32:47], v[100:103], v[108:111], v[32:47]
	ds_read_b128 v[100:103], v81 offset:36864
	s_waitcnt lgkmcnt(0)
	v_mfma_f32_32x32x16_bf16 v[16:31], v[100:103], v[104:107], v[16:31]
	v_mfma_f32_32x32x16_bf16 v[0:15], v[100:103], v[108:111], v[0:15]
	ds_read_b128 v[100:103], v84 offset:32768
	ds_read_b128 v[104:107], v85 offset:49152
	ds_read_b128 v[108:111], v85 offset:53248
	s_waitcnt lgkmcnt(0)
	v_mfma_f32_32x32x16_bf16 v[48:63], v[100:103], v[104:107], v[48:63]
	v_mfma_f32_32x32x16_bf16 v[32:47], v[100:103], v[108:111], v[32:47]
	ds_read_b128 v[100:103], v84 offset:36864
	s_waitcnt lgkmcnt(0)
	v_mfma_f32_32x32x16_bf16 v[16:31], v[100:103], v[104:107], v[16:31]
	v_mfma_f32_32x32x16_bf16 v[0:15], v[100:103], v[108:111], v[0:15]
	ds_read_b128 v[100:103], v86 offset:32768
	ds_read_b128 v[104:107], v87 offset:49152
	ds_read_b128 v[108:111], v87 offset:53248
	s_waitcnt lgkmcnt(0)
	v_mfma_f32_32x32x16_bf16 v[48:63], v[100:103], v[104:107], v[48:63]
	v_mfma_f32_32x32x16_bf16 v[32:47], v[100:103], v[108:111], v[32:47]
	ds_read_b128 v[100:103], v86 offset:36864
	s_waitcnt vmcnt(0)
	s_waitcnt vmcnt(0) lgkmcnt(0)
	s_barrier
; #define WAIT_V0() asm volatile("s_waitcnt vmcnt(0)" ::: "memory")
; DI void gemm_core(char* smem, int nk, const char* Ab, const char* Bb, const unsigned (&aoff)[4], const unsigned (&boff)[4],
;                   f32x16 (&acc)[2][2]) {
;     ...
;   for (int kt = 0; kt < nk; ++kt) {
;     const int cur = kt & 1;
;     if (kt + 1 < nk) stage(cur ^ 1, kt + 1);
;     const char* sb = smem + cur * STAGE_B;
; #pragma unroll
;     for (int ks = 0; ks < 4; ++ks) {
;       bf16x8 af[2], bfr[2];
; #pragma unroll
;       for (int mb = 0; mb < 2; ++mb) af[mb] = *(const bf16x8*)(sb + a_base + mb * 4096 + xo[ks]);
; #pragma unroll
;       for (int nb = 0; nb < 2; ++nb) bfr[nb] = *(const bf16x8*)(sb + b_base + nb * 4096 + xo[ks]);
; #pragma unroll
;       for (int mb = 0; mb < 2; ++mb)
; #pragma unroll
;         for (int nb = 0; nb < 2; ++nb)
;           acc[mb][nb] = __builtin_amdgcn_mfma_f32_32x32x16_bf16(af[mb], bfr[nb], acc[mb][nb], 0, 0, 0);
;     }
;     WAIT_V0();
;     __syncthreads();
;   }
	v_mfma_f32_32x32x16_bf16 v[16:31], v[100:103], v[104:107], v[16:31]
	v_mfma_f32_32x32x16_bf16 v[0:15], v[100:103], v[108:111], v[0:15]
	v_lshl_add_u64 v[100:101], v[64:65], 0, s[38:39]
	global_load_lds_dwordx4 v[100:101], off
	v_lshl_add_u64 v[100:101], v[66:67], 0, s[38:39]
	s_mov_b32 m0, s43
	s_nop 0
	global_load_lds_dwordx4 v[100:101], off
	v_lshl_add_u64 v[100:101], v[68:69], 0, s[38:39]
	s_mov_b32 m0, s44
	s_nop 0
	global_load_lds_dwordx4 v[100:101], off
	v_lshl_add_u64 v[100:101], v[70:71], 0, s[38:39]
	s_mov_b32 m0, s1
	s_nop 0
	global_load_lds_dwordx4 v[100:101], off
	v_lshl_add_u64 v[100:101], v[72:73], 0, s[38:39]
	s_mov_b32 m0, s16
	s_nop 0
	global_load_lds_dwordx4 v[100:101], off
	v_lshl_add_u64 v[100:101], v[74:75], 0, s[38:39]
	s_mov_b32 m0, s17
	s_nop 0
	global_load_lds_dwordx4 v[100:101], off
	v_lshl_add_u64 v[100:101], v[76:77], 0, s[38:39]
	s_mov_b32 m0, s18
	s_nop 0
	global_load_lds_dwordx4 v[100:101], off
	v_lshl_add_u64 v[100:101], v[78:79], 0, s[38:39]
	s_mov_b32 m0, s19
	s_nop 0
	global_load_lds_dwordx4 v[100:101], off
	ds_read_b128 v[100:103], v80
	ds_read_b128 v[104:107], v82 offset:16384
	ds_read_b128 v[108:111], v82 offset:20480
	s_waitcnt lgkmcnt(0)
	v_mfma_f32_32x32x16_bf16 v[48:63], v[100:103], v[104:107], v[48:63]
	s_mov_b32 m0, s20
	v_mfma_f32_32x32x16_bf16 v[32:47], v[100:103], v[108:111], v[32:47]
	ds_read_b128 v[100:103], v80 offset:4096
	s_waitcnt lgkmcnt(0)
	v_mfma_f32_32x32x16_bf16 v[16:31], v[100:103], v[104:107], v[16:31]
	v_mfma_f32_32x32x16_bf16 v[0:15], v[100:103], v[108:111], v[0:15]
	ds_read_b128 v[100:103], v81
	ds_read_b128 v[104:107], v83 offset:16384
	ds_read_b128 v[108:111], v83 offset:20480
	s_waitcnt lgkmcnt(0)
	v_mfma_f32_32x32x16_bf16 v[48:63], v[100:103], v[104:107], v[48:63]
	v_mfma_f32_32x32x16_bf16 v[32:47], v[100:103], v[108:111], v[32:47]
	ds_read_b128 v[100:103], v81 offset:4096
	s_waitcnt lgkmcnt(0)
	v_mfma_f32_32x32x16_bf16 v[16:31], v[100:103], v[104:107], v[16:31]
	v_mfma_f32_32x32x16_bf16 v[0:15], v[100:103], v[108:111], v[0:15]
	ds_read_b128 v[100:103], v84
	ds_read_b128 v[104:107], v85 offset:16384
	ds_read_b128 v[108:111], v85 offset:20480
	s_waitcnt lgkmcnt(0)
	v_mfma_f32_32x32x16_bf16 v[48:63], v[100:103], v[104:107], v[48:63]
	v_mfma_f32_32x32x16_bf16 v[32:47], v[100:103], v[108:111], v[32:47]
	ds_read_b128 v[100:103], v84 offset:4096
	s_waitcnt lgkmcnt(0)
	v_mfma_f32_32x32x16_bf16 v[16:31], v[100:103], v[104:107], v[16:31]
	v_mfma_f32_32x32x16_bf16 v[0:15], v[100:103], v[108:111], v[0:15]
	ds_read_b128 v[100:103], v86
	ds_read_b128 v[104:107], v87 offset:16384
	ds_read_b128 v[108:111], v87 offset:20480
	s_waitcnt lgkmcnt(0)
	v_mfma_f32_32x32x16_bf16 v[48:63], v[100:103], v[104:107], v[48:63]
	v_mfma_f32_32x32x16_bf16 v[32:47], v[100:103], v[108:111], v[32:47]
	ds_read_b128 v[100:103], v86 offset:4096
	s_waitcnt vmcnt(0)
	s_waitcnt vmcnt(0) lgkmcnt(0)
	s_barrier
	v_mfma_f32_32x32x16_bf16 v[16:31], v[100:103], v[104:107], v[16:31]
	v_mfma_f32_32x32x16_bf16 v[0:15], v[100:103], v[108:111], v[0:15]
	v_lshl_add_u64 v[100:101], v[64:65], 0, s[30:31]
	global_load_lds_dwordx4 v[100:101], off
	v_lshl_add_u64 v[100:101], v[66:67], 0, s[30:31]
	s_mov_b32 m0, s21
	s_nop 0
	global_load_lds_dwordx4 v[100:101], off
	v_lshl_add_u64 v[100:101], v[68:69], 0, s[30:31]
	s_mov_b32 m0, s22
	s_nop 0
	global_load_lds_dwordx4 v[100:101], off
	v_lshl_add_u64 v[100:101], v[70:71], 0, s[30:31]
	s_mov_b32 m0, s23
	s_nop 0
	global_load_lds_dwordx4 v[100:101], off
	v_lshl_add_u64 v[100:101], v[72:73], 0, s[30:31]
	s_mov_b32 m0, s28
	s_nop 0
	global_load_lds_dwordx4 v[100:101], off
	v_lshl_add_u64 v[100:101], v[74:75], 0, s[30:31]
	s_mov_b32 m0, s29
	s_nop 0
	global_load_lds_dwordx4 v[100:101], off
	v_lshl_add_u64 v[100:101], v[76:77], 0, s[30:31]
	s_mov_b32 m0, s40
	s_nop 0
	global_load_lds_dwordx4 v[100:101], off
	v_lshl_add_u64 v[100:101], v[78:79], 0, s[30:31]
	s_mov_b32 m0, s41
	s_nop 0
	global_load_lds_dwordx4 v[100:101], off
	ds_read_b128 v[100:103], v80 offset:32768
	ds_read_b128 v[104:107], v82 offset:49152
	ds_read_b128 v[108:111], v82 offset:53248
	s_waitcnt lgkmcnt(0)
	v_mfma_f32_32x32x16_bf16 v[48:63], v[100:103], v[104:107], v[48:63]
	s_mov_b32 m0, s42
	v_mfma_f32_32x32x16_bf16 v[32:47], v[100:103], v[108:111], v[32:47]
	ds_read_b128 v[100:103], v80 offset:36864
	s_waitcnt lgkmcnt(0)
	v_mfma_f32_32x32x16_bf16 v[16:31], v[100:103], v[104:107], v[16:31]
	v_mfma_f32_32x32x16_bf16 v[0:15], v[100:103], v[108:111], v[0:15]
	ds_read_b128 v[100:103], v81 offset:32768
	ds_read_b128 v[104:107], v83 offset:49152
	ds_read_b128 v[108:111], v83 offset:53248
	s_waitcnt lgkmcnt(0)
	v_mfma_f32_32x32x16_bf16 v[48:63], v[100:103], v[104:107], v[48:63]
	v_mfma_f32_32x32x16_bf16 v[32:47], v[100:103], v[108:111], v[32:47]
	ds_read_b128 v[100:103], v81 offset:36864
	s_waitcnt lgkmcnt(0)
	v_mfma_f32_32x32x16_bf16 v[16:31], v[100:103], v[104:107], v[16:31]
	v_mfma_f32_32x32x16_bf16 v[0:15], v[100:103], v[108:111], v[0:15]
	ds_read_b128 v[100:103], v84 offset:32768
	ds_read_b128 v[104:107], v85 offset:49152
	ds_read_b128 v[108:111], v85 offset:53248
	s_waitcnt lgkmcnt(0)
	v_mfma_f32_32x32x16_bf16 v[48:63], v[100:103], v[104:107], v[48:63]
	v_mfma_f32_32x32x16_bf16 v[32:47], v[100:103], v[108:111], v[32:47]
	ds_read_b128 v[100:103], v84 offset:36864
	s_waitcnt lgkmcnt(0)
	v_mfma_f32_32x32x16_bf16 v[16:31], v[100:103], v[104:107], v[16:31]
	v_mfma_f32_32x32x16_bf16 v[0:15], v[100:103], v[108:111], v[0:15]
	ds_read_b128 v[100:103], v86 offset:32768
	ds_read_b128 v[104:107], v87 offset:49152
	ds_read_b128 v[108:111], v87 offset:53248
	s_waitcnt lgkmcnt(0)
	v_mfma_f32_32x32x16_bf16 v[48:63], v[100:103], v[104:107], v[48:63]
	v_mfma_f32_32x32x16_bf16 v[32:47], v[100:103], v[108:111], v[32:47]
	ds_read_b128 v[100:103], v86 offset:36864
	s_waitcnt vmcnt(0)
	s_waitcnt vmcnt(0) lgkmcnt(0)
	s_barrier
; #define WAIT_V0() asm volatile("s_waitcnt vmcnt(0)" ::: "memory")
; DI void gemm_core(char* smem, int nk, const char* Ab, const char* Bb, const unsigned (&aoff)[4], const unsigned (&boff)[4],
;                   f32x16 (&acc)[2][2]) {
;     ...
;   for (int kt = 0; kt < nk; ++kt) {
;     const int cur = kt & 1;
;     if (kt + 1 < nk) stage(cur ^ 1, kt + 1);
;     const char* sb = smem + cur * STAGE_B;
; #pragma unroll
;     for (int ks = 0; ks < 4; ++ks) {
;       bf16x8 af[2], bfr[2];
; #pragma unroll
;       for (int mb = 0; mb < 2; ++mb) af[mb] = *(const bf16x8*)(sb + a_base + mb * 4096 + xo[ks]);
; #pragma unroll
;       for (int nb = 0; nb < 2; ++nb) bfr[nb] = *(const bf16x8*)(sb + b_base + nb * 4096 + xo[ks]);
; #pragma unroll
;       for (int mb = 0; mb < 2; ++mb)
; #pragma unroll
;         for (int nb = 0; nb < 2; ++nb)
;           acc[mb][nb] = __builtin_amdgcn_mfma_f32_32x32x16_bf16(af[mb], bfr[nb], acc[mb][nb], 0, 0, 0);
;     }
;     WAIT_V0();
;     __syncthreads();
;   }
	v_mfma_f32_32x32x16_bf16 v[16:31], v[100:103], v[104:107], v[16:31]
	v_mfma_f32_32x32x16_bf16 v[0:15], v[100:103], v[108:111], v[0:15]
	v_lshl_add_u64 v[100:101], v[64:65], 0, s[46:47]
	global_load_lds_dwordx4 v[100:101], off
	v_lshl_add_u64 v[100:101], v[66:67], 0, s[46:47]
	s_mov_b32 m0, s43
	s_nop 0
	global_load_lds_dwordx4 v[100:101], off
	v_lshl_add_u64 v[100:101], v[68:69], 0, s[46:47]
	s_mov_b32 m0, s44
	s_nop 0
	global_load_lds_dwordx4 v[100:101], off
	v_lshl_add_u64 v[100:101], v[70:71], 0, s[46:47]
	s_mov_b32 m0, s1
	s_nop 0
	global_load_lds_dwordx4 v[100:101], off
	v_lshl_add_u64 v[100:101], v[72:73], 0, s[46:47]
	s_mov_b32 m0, s16
	s_nop 0
	global_load_lds_dwordx4 v[100:101], off
	v_lshl_add_u64 v[100:101], v[74:75], 0, s[46:47]
	s_mov_b32 m0, s17
	s_nop 0
	global_load_lds_dwordx4 v[100:101], off
	v_lshl_add_u64 v[100:101], v[76:77], 0, s[46:47]
	s_mov_b32 m0, s18
	s_nop 0
	global_load_lds_dwordx4 v[100:101], off
	v_lshl_add_u64 v[100:101], v[78:79], 0, s[46:47]
	s_mov_b32 m0, s19
	s_nop 0
	global_load_lds_dwordx4 v[100:101], off
	ds_read_b128 v[100:103], v80
	ds_read_b128 v[104:107], v82 offset:16384
	ds_read_b128 v[108:111], v82 offset:20480
	s_waitcnt lgkmcnt(0)
	v_mfma_f32_32x32x16_bf16 v[48:63], v[100:103], v[104:107], v[48:63]
	s_mov_b32 m0, s20
	v_mfma_f32_32x32x16_bf16 v[32:47], v[100:103], v[108:111], v[32:47]
	ds_read_b128 v[100:103], v80 offset:4096
	s_waitcnt lgkmcnt(0)
	v_mfma_f32_32x32x16_bf16 v[16:31], v[100:103], v[104:107], v[16:31]
	v_mfma_f32_32x32x16_bf16 v[0:15], v[100:103], v[108:111], v[0:15]
	ds_read_b128 v[100:103], v81
	ds_read_b128 v[104:107], v83 offset:16384
	ds_read_b128 v[108:111], v83 offset:20480
	s_waitcnt lgkmcnt(0)
	v_mfma_f32_32x32x16_bf16 v[48:63], v[100:103], v[104:107], v[48:63]
	v_mfma_f32_32x32x16_bf16 v[32:47], v[100:103], v[108:111], v[32:47]
	ds_read_b128 v[100:103], v81 offset:4096
	s_waitcnt lgkmcnt(0)
	v_mfma_f32_32x32x16_bf16 v[16:31], v[100:103], v[104:107], v[16:31]
	v_mfma_f32_32x32x16_bf16 v[0:15], v[100:103], v[108:111], v[0:15]
	ds_read_b128 v[100:103], v84
	ds_read_b128 v[104:107], v85 offset:16384
	ds_read_b128 v[108:111], v85 offset:20480
	s_waitcnt lgkmcnt(0)
	v_mfma_f32_32x32x16_bf16 v[48:63], v[100:103], v[104:107], v[48:63]
	v_mfma_f32_32x32x16_bf16 v[32:47], v[100:103], v[108:111], v[32:47]
	ds_read_b128 v[100:103], v84 offset:4096
	s_waitcnt lgkmcnt(0)
	v_mfma_f32_32x32x16_bf16 v[16:31], v[100:103], v[104:107], v[16:31]
	v_mfma_f32_32x32x16_bf16 v[0:15], v[100:103], v[108:111], v[0:15]
	ds_read_b128 v[100:103], v86
	ds_read_b128 v[104:107], v87 offset:16384
	ds_read_b128 v[108:111], v87 offset:20480
	s_waitcnt lgkmcnt(0)
	v_mfma_f32_32x32x16_bf16 v[48:63], v[100:103], v[104:107], v[48:63]
	v_mfma_f32_32x32x16_bf16 v[32:47], v[100:103], v[108:111], v[32:47]
	ds_read_b128 v[100:103], v86 offset:4096
	s_waitcnt vmcnt(0)
	s_waitcnt vmcnt(0) lgkmcnt(0)
	s_barrier
	v_mfma_f32_32x32x16_bf16 v[16:31], v[100:103], v[104:107], v[16:31]
	v_mfma_f32_32x32x16_bf16 v[0:15], v[100:103], v[108:111], v[0:15]
	v_lshl_add_u64 v[100:101], v[64:65], 0, s[48:49]
	global_load_lds_dwordx4 v[100:101], off
	v_lshl_add_u64 v[100:101], v[66:67], 0, s[48:49]
	s_mov_b32 m0, s21
	s_nop 0
	global_load_lds_dwordx4 v[100:101], off
	v_lshl_add_u64 v[100:101], v[68:69], 0, s[48:49]
	s_mov_b32 m0, s22
	s_nop 0
	global_load_lds_dwordx4 v[100:101], off
	v_lshl_add_u64 v[100:101], v[70:71], 0, s[48:49]
	s_mov_b32 m0, s23
	s_nop 0
	global_load_lds_dwordx4 v[100:101], off
	v_lshl_add_u64 v[100:101], v[72:73], 0, s[48:49]
	s_mov_b32 m0, s28
	s_nop 0
	global_load_lds_dwordx4 v[100:101], off
	v_lshl_add_u64 v[100:101], v[74:75], 0, s[48:49]
	s_mov_b32 m0, s29
	s_nop 0
	global_load_lds_dwordx4 v[100:101], off
	v_lshl_add_u64 v[100:101], v[76:77], 0, s[48:49]
	s_mov_b32 m0, s40
	s_nop 0
	global_load_lds_dwordx4 v[100:101], off
	v_lshl_add_u64 v[100:101], v[78:79], 0, s[48:49]
	s_mov_b32 m0, s41
	s_nop 0
	global_load_lds_dwordx4 v[100:101], off
	ds_read_b128 v[100:103], v80 offset:32768
	ds_read_b128 v[104:107], v82 offset:49152
	ds_read_b128 v[108:111], v82 offset:53248
	s_waitcnt lgkmcnt(0)
	v_mfma_f32_32x32x16_bf16 v[48:63], v[100:103], v[104:107], v[48:63]
	s_mov_b32 m0, s42
	v_readfirstlane_b32 s42, v93
	v_mfma_f32_32x32x16_bf16 v[32:47], v[100:103], v[108:111], v[32:47]
	ds_read_b128 v[100:103], v80 offset:36864
	s_waitcnt lgkmcnt(0)
	v_mfma_f32_32x32x16_bf16 v[16:31], v[100:103], v[104:107], v[16:31]
	v_mfma_f32_32x32x16_bf16 v[0:15], v[100:103], v[108:111], v[0:15]
	ds_read_b128 v[100:103], v81 offset:32768
	ds_read_b128 v[104:107], v83 offset:49152
	ds_read_b128 v[108:111], v83 offset:53248
	s_waitcnt lgkmcnt(0)
	v_mfma_f32_32x32x16_bf16 v[48:63], v[100:103], v[104:107], v[48:63]
	v_mfma_f32_32x32x16_bf16 v[32:47], v[100:103], v[108:111], v[32:47]
	ds_read_b128 v[100:103], v81 offset:36864
	s_waitcnt lgkmcnt(0)
	v_mfma_f32_32x32x16_bf16 v[16:31], v[100:103], v[104:107], v[16:31]
	v_mfma_f32_32x32x16_bf16 v[0:15], v[100:103], v[108:111], v[0:15]
	ds_read_b128 v[100:103], v84 offset:32768
	ds_read_b128 v[104:107], v85 offset:49152
	ds_read_b128 v[108:111], v85 offset:53248
	s_waitcnt lgkmcnt(0)
	v_mfma_f32_32x32x16_bf16 v[48:63], v[100:103], v[104:107], v[48:63]
	v_mfma_f32_32x32x16_bf16 v[32:47], v[100:103], v[108:111], v[32:47]
	ds_read_b128 v[100:103], v84 offset:36864
	s_waitcnt lgkmcnt(0)
	v_mfma_f32_32x32x16_bf16 v[16:31], v[100:103], v[104:107], v[16:31]
	v_mfma_f32_32x32x16_bf16 v[0:15], v[100:103], v[108:111], v[0:15]
	ds_read_b128 v[100:103], v86 offset:32768
	ds_read_b128 v[104:107], v87 offset:49152
	ds_read_b128 v[108:111], v87 offset:53248
	s_waitcnt lgkmcnt(0)
	v_mfma_f32_32x32x16_bf16 v[48:63], v[100:103], v[104:107], v[48:63]
	v_mfma_f32_32x32x16_bf16 v[32:47], v[100:103], v[108:111], v[32:47]
	ds_read_b128 v[100:103], v86 offset:36864
	s_waitcnt vmcnt(0)
	s_waitcnt vmcnt(0) lgkmcnt(0)
	s_barrier
; #define WAIT_V0() asm volatile("s_waitcnt vmcnt(0)" ::: "memory")
; DI void gemm_core(char* smem, int nk, const char* Ab, const char* Bb, const unsigned (&aoff)[4], const unsigned (&boff)[4],
;                   f32x16 (&acc)[2][2]) {
;     ...
;   for (int kt = 0; kt < nk; ++kt) {
;     const int cur = kt & 1;
;     if (kt + 1 < nk) stage(cur ^ 1, kt + 1);
;     const char* sb = smem + cur * STAGE_B;
; #pragma unroll
;     for (int ks = 0; ks < 4; ++ks) {
;       bf16x8 af[2], bfr[2];
; #pragma unroll
;       for (int mb = 0; mb < 2; ++mb) af[mb] = *(const bf16x8*)(sb + a_base + mb * 4096 + xo[ks]);
; #pragma unroll
;       for (int nb = 0; nb < 2; ++nb) bfr[nb] = *(const bf16x8*)(sb + b_base + nb * 4096 + xo[ks]);
; #pragma unroll
;       for (int mb = 0; mb < 2; ++mb)
; #pragma unroll
;         for (int nb = 0; nb < 2; ++nb)
;           acc[mb][nb] = __builtin_amdgcn_mfma_f32_32x32x16_bf16(af[mb], bfr[nb], acc[mb][nb], 0, 0, 0);
;     }
;     WAIT_V0();
;     __syncthreads();
;   }
	v_mfma_f32_32x32x16_bf16 v[16:31], v[100:103], v[104:107], v[16:31]
	v_mfma_f32_32x32x16_bf16 v[0:15], v[100:103], v[108:111], v[0:15]
	v_lshl_add_u64 v[100:101], v[64:65], 0, s[50:51]
	global_load_lds_dwordx4 v[100:101], off
	v_lshl_add_u64 v[100:101], v[66:67], 0, s[50:51]
	s_mov_b32 m0, s43
	v_readfirstlane_b32 s43, v94
	global_load_lds_dwordx4 v[100:101], off
	v_lshl_add_u64 v[100:101], v[68:69], 0, s[50:51]
	s_mov_b32 m0, s44
	v_readfirstlane_b32 s44, v95
	global_load_lds_dwordx4 v[100:101], off
	v_lshl_add_u64 v[100:101], v[70:71], 0, s[50:51]
	s_mov_b32 m0, s1
	s_nop 0
	global_load_lds_dwordx4 v[100:101], off
	v_lshl_add_u64 v[100:101], v[72:73], 0, s[50:51]
	s_mov_b32 m0, s16
	s_nop 0
	global_load_lds_dwordx4 v[100:101], off
	v_lshl_add_u64 v[100:101], v[74:75], 0, s[50:51]
	s_mov_b32 m0, s17
	s_nop 0
	global_load_lds_dwordx4 v[100:101], off
	v_lshl_add_u64 v[100:101], v[76:77], 0, s[50:51]
	s_mov_b32 m0, s18
	s_nop 0
	global_load_lds_dwordx4 v[100:101], off
	v_lshl_add_u64 v[100:101], v[78:79], 0, s[50:51]
	s_mov_b32 m0, s19
	s_nop 0
	global_load_lds_dwordx4 v[100:101], off
	ds_read_b128 v[100:103], v80
	ds_read_b128 v[104:107], v82 offset:16384
	ds_read_b128 v[108:111], v82 offset:20480
	s_waitcnt lgkmcnt(0)
	v_mfma_f32_32x32x16_bf16 v[48:63], v[100:103], v[104:107], v[48:63]
	s_mov_b32 m0, s20
	v_readfirstlane_b32 s20, v97
	v_mfma_f32_32x32x16_bf16 v[32:47], v[100:103], v[108:111], v[32:47]
	ds_read_b128 v[100:103], v80 offset:4096
	s_waitcnt lgkmcnt(0)
	v_mfma_f32_32x32x16_bf16 v[16:31], v[100:103], v[104:107], v[16:31]
	v_mfma_f32_32x32x16_bf16 v[0:15], v[100:103], v[108:111], v[0:15]
	ds_read_b128 v[100:103], v81
	ds_read_b128 v[104:107], v83 offset:16384
	ds_read_b128 v[108:111], v83 offset:20480
	s_waitcnt lgkmcnt(0)
	v_mfma_f32_32x32x16_bf16 v[48:63], v[100:103], v[104:107], v[48:63]
	v_mfma_f32_32x32x16_bf16 v[32:47], v[100:103], v[108:111], v[32:47]
	ds_read_b128 v[100:103], v81 offset:4096
	s_waitcnt lgkmcnt(0)
	v_mfma_f32_32x32x16_bf16 v[16:31], v[100:103], v[104:107], v[16:31]
	v_mfma_f32_32x32x16_bf16 v[0:15], v[100:103], v[108:111], v[0:15]
	ds_read_b128 v[100:103], v84
	ds_read_b128 v[104:107], v85 offset:16384
	ds_read_b128 v[108:111], v85 offset:20480
	s_waitcnt lgkmcnt(0)
	v_mfma_f32_32x32x16_bf16 v[48:63], v[100:103], v[104:107], v[48:63]
	v_mfma_f32_32x32x16_bf16 v[32:47], v[100:103], v[108:111], v[32:47]
	ds_read_b128 v[100:103], v84 offset:4096
	s_waitcnt lgkmcnt(0)
	v_mfma_f32_32x32x16_bf16 v[16:31], v[100:103], v[104:107], v[16:31]
	v_mfma_f32_32x32x16_bf16 v[0:15], v[100:103], v[108:111], v[0:15]
	ds_read_b128 v[100:103], v86
	ds_read_b128 v[104:107], v87 offset:16384
	ds_read_b128 v[108:111], v87 offset:20480
	s_waitcnt lgkmcnt(0)
	v_mfma_f32_32x32x16_bf16 v[48:63], v[100:103], v[104:107], v[48:63]
	v_mfma_f32_32x32x16_bf16 v[32:47], v[100:103], v[108:111], v[32:47]
	ds_read_b128 v[100:103], v86 offset:4096
	s_waitcnt vmcnt(0)
	s_waitcnt vmcnt(0) lgkmcnt(0)
	s_barrier
	v_mfma_f32_32x32x16_bf16 v[16:31], v[100:103], v[104:107], v[16:31]
	v_mfma_f32_32x32x16_bf16 v[0:15], v[100:103], v[108:111], v[0:15]
	v_lshl_add_u64 v[100:101], v[64:65], 0, s[52:53]
	global_load_lds_dwordx4 v[100:101], off
	v_lshl_add_u64 v[100:101], v[66:67], 0, s[52:53]
	s_mov_b32 m0, s21
	v_readfirstlane_b32 s21, v96
	global_load_lds_dwordx4 v[100:101], off
	v_lshl_add_u64 v[100:101], v[68:69], 0, s[52:53]
	s_mov_b32 m0, s22
	v_readfirstlane_b32 s22, v98
	global_load_lds_dwordx4 v[100:101], off
	v_lshl_add_u64 v[100:101], v[70:71], 0, s[52:53]
	s_mov_b32 m0, s23
	v_lshl_add_u64 v[96:97], v[68:69], 0, s[54:55]
	global_load_lds_dwordx4 v[100:101], off
	v_lshl_add_u64 v[100:101], v[72:73], 0, s[52:53]
	s_mov_b32 m0, s28
	v_readfirstlane_b32 s23, v89
	global_load_lds_dwordx4 v[100:101], off
	v_lshl_add_u64 v[100:101], v[74:75], 0, s[52:53]
	s_mov_b32 m0, s29
	v_readfirstlane_b32 s28, v88
	global_load_lds_dwordx4 v[100:101], off
	v_lshl_add_u64 v[100:101], v[76:77], 0, s[52:53]
	s_mov_b32 m0, s40
	v_readfirstlane_b32 s29, v90
	global_load_lds_dwordx4 v[100:101], off
	v_lshl_add_u64 v[100:101], v[78:79], 0, s[52:53]
	s_mov_b32 m0, s41
	v_lshl_add_u64 v[88:89], v[68:69], 0, s[56:57]
	global_load_lds_dwordx4 v[100:101], off
	ds_read_b128 v[100:103], v80 offset:32768
	ds_read_b128 v[104:107], v82 offset:49152
	ds_read_b128 v[108:111], v82 offset:53248
	s_waitcnt lgkmcnt(0)
	v_mfma_f32_32x32x16_bf16 v[48:63], v[100:103], v[104:107], v[48:63]
	s_mov_b32 m0, s20
	v_readfirstlane_b32 s40, v91
	v_readfirstlane_b32 s41, v92
	v_mfma_f32_32x32x16_bf16 v[32:47], v[100:103], v[108:111], v[32:47]
	ds_read_b128 v[100:103], v80 offset:36864
	s_waitcnt lgkmcnt(0)
	v_mfma_f32_32x32x16_bf16 v[16:31], v[100:103], v[104:107], v[16:31]
	v_mfma_f32_32x32x16_bf16 v[0:15], v[100:103], v[108:111], v[0:15]
	ds_read_b128 v[100:103], v81 offset:32768
	ds_read_b128 v[104:107], v83 offset:49152
	ds_read_b128 v[108:111], v83 offset:53248
	s_waitcnt lgkmcnt(0)
	v_mfma_f32_32x32x16_bf16 v[48:63], v[100:103], v[104:107], v[48:63]
	v_mfma_f32_32x32x16_bf16 v[32:47], v[100:103], v[108:111], v[32:47]
	ds_read_b128 v[100:103], v81 offset:36864
	s_waitcnt lgkmcnt(0)
	v_mfma_f32_32x32x16_bf16 v[16:31], v[100:103], v[104:107], v[16:31]
	v_mfma_f32_32x32x16_bf16 v[0:15], v[100:103], v[108:111], v[0:15]
	ds_read_b128 v[100:103], v84 offset:32768
	ds_read_b128 v[104:107], v85 offset:49152
	ds_read_b128 v[108:111], v85 offset:53248
	s_waitcnt lgkmcnt(0)
	v_mfma_f32_32x32x16_bf16 v[48:63], v[100:103], v[104:107], v[48:63]
	v_mfma_f32_32x32x16_bf16 v[32:47], v[100:103], v[108:111], v[32:47]
	ds_read_b128 v[100:103], v84 offset:36864
	s_waitcnt lgkmcnt(0)
	v_mfma_f32_32x32x16_bf16 v[16:31], v[100:103], v[104:107], v[16:31]
	v_mfma_f32_32x32x16_bf16 v[0:15], v[100:103], v[108:111], v[0:15]
	ds_read_b128 v[100:103], v86 offset:32768
	ds_read_b128 v[104:107], v87 offset:49152
	ds_read_b128 v[108:111], v87 offset:53248
	s_waitcnt lgkmcnt(0)
	v_mfma_f32_32x32x16_bf16 v[48:63], v[100:103], v[104:107], v[48:63]
	v_mfma_f32_32x32x16_bf16 v[32:47], v[100:103], v[108:111], v[32:47]
	ds_read_b128 v[100:103], v86 offset:36864
	s_waitcnt vmcnt(0)
	s_waitcnt vmcnt(0) lgkmcnt(0)
	s_barrier
; #define WAIT_V0() asm volatile("s_waitcnt vmcnt(0)" ::: "memory")
; DI void gemm_core(char* smem, int nk, const char* Ab, const char* Bb, const unsigned (&aoff)[4], const unsigned (&boff)[4],
;                   f32x16 (&acc)[2][2]) {
;     ...
;   for (int kt = 0; kt < nk; ++kt) {
;     const int cur = kt & 1;
;     if (kt + 1 < nk) stage(cur ^ 1, kt + 1);
;     const char* sb = smem + cur * STAGE_B;
; #pragma unroll
;     for (int ks = 0; ks < 4; ++ks) {
;       bf16x8 af[2], bfr[2];
; #pragma unroll
;       for (int mb = 0; mb < 2; ++mb) af[mb] = *(const bf16x8*)(sb + a_base + mb * 4096 + xo[ks]);
; #pragma unroll
;       for (int nb = 0; nb < 2; ++nb) bfr[nb] = *(const bf16x8*)(sb + b_base + nb * 4096 + xo[ks]);
; #pragma unroll
;       for (int mb = 0; mb < 2; ++mb)
; #pragma unroll
;         for (int nb = 0; nb < 2; ++nb)
;           acc[mb][nb] = __builtin_amdgcn_mfma_f32_32x32x16_bf16(af[mb], bfr[nb], acc[mb][nb], 0, 0, 0);
;     }
;     WAIT_V0();
;     __syncthreads();
;   }
	v_mfma_f32_32x32x16_bf16 v[16:31], v[100:103], v[104:107], v[16:31]
	v_mfma_f32_32x32x16_bf16 v[0:15], v[100:103], v[108:111], v[0:15]
	v_lshl_add_u64 v[100:101], v[64:65], 0, s[54:55]
	global_load_lds_dwordx4 v[100:101], off
	v_lshl_add_u64 v[100:101], v[66:67], 0, s[54:55]
	s_mov_b32 m0, s21
	s_nop 0
	global_load_lds_dwordx4 v[100:101], off
	s_mov_b32 m0, s22
	s_nop 0
	global_load_lds_dwordx4 v[96:97], off
	v_lshl_add_u64 v[96:97], v[70:71], 0, s[54:55]
	s_mov_b32 m0, s1
	s_nop 0
	global_load_lds_dwordx4 v[96:97], off
	v_lshl_add_u64 v[96:97], v[72:73], 0, s[54:55]
	s_mov_b32 m0, s16
	s_nop 0
	global_load_lds_dwordx4 v[96:97], off
	v_lshl_add_u64 v[96:97], v[74:75], 0, s[54:55]
	s_mov_b32 m0, s17
	s_nop 0
	global_load_lds_dwordx4 v[96:97], off
	v_lshl_add_u64 v[96:97], v[76:77], 0, s[54:55]
	s_mov_b32 m0, s18
	s_nop 0
	global_load_lds_dwordx4 v[96:97], off
	v_lshl_add_u64 v[96:97], v[78:79], 0, s[54:55]
	s_mov_b32 m0, s19
	s_nop 0
	global_load_lds_dwordx4 v[96:97], off
	ds_read_b128 v[96:99], v80
	ds_read_b128 v[100:103], v82 offset:16384
	ds_read_b128 v[104:107], v82 offset:20480
	s_waitcnt lgkmcnt(0)
	v_mfma_f32_32x32x16_bf16 v[48:63], v[96:99], v[100:103], v[48:63]
	s_mov_b32 m0, s23
	v_mfma_f32_32x32x16_bf16 v[32:47], v[96:99], v[104:107], v[32:47]
	ds_read_b128 v[96:99], v80 offset:4096
	s_waitcnt lgkmcnt(0)
	v_mfma_f32_32x32x16_bf16 v[16:31], v[96:99], v[100:103], v[16:31]
	v_mfma_f32_32x32x16_bf16 v[0:15], v[96:99], v[104:107], v[0:15]
	ds_read_b128 v[96:99], v81
	ds_read_b128 v[100:103], v83 offset:16384
	ds_read_b128 v[104:107], v83 offset:20480
	s_waitcnt lgkmcnt(0)
	v_mfma_f32_32x32x16_bf16 v[48:63], v[96:99], v[100:103], v[48:63]
	v_mfma_f32_32x32x16_bf16 v[32:47], v[96:99], v[104:107], v[32:47]
	ds_read_b128 v[96:99], v81 offset:4096
	s_waitcnt lgkmcnt(0)
	v_mfma_f32_32x32x16_bf16 v[16:31], v[96:99], v[100:103], v[16:31]
	v_mfma_f32_32x32x16_bf16 v[0:15], v[96:99], v[104:107], v[0:15]
	ds_read_b128 v[96:99], v84
	ds_read_b128 v[100:103], v85 offset:16384
	ds_read_b128 v[104:107], v85 offset:20480
	s_waitcnt lgkmcnt(0)
	v_mfma_f32_32x32x16_bf16 v[48:63], v[96:99], v[100:103], v[48:63]
	v_mfma_f32_32x32x16_bf16 v[32:47], v[96:99], v[104:107], v[32:47]
	ds_read_b128 v[96:99], v84 offset:4096
	s_waitcnt lgkmcnt(0)
	v_mfma_f32_32x32x16_bf16 v[16:31], v[96:99], v[100:103], v[16:31]
	v_mfma_f32_32x32x16_bf16 v[0:15], v[96:99], v[104:107], v[0:15]
	ds_read_b128 v[96:99], v86
	ds_read_b128 v[100:103], v87 offset:16384
	ds_read_b128 v[104:107], v87 offset:20480
	s_waitcnt lgkmcnt(0)
	v_mfma_f32_32x32x16_bf16 v[48:63], v[96:99], v[100:103], v[48:63]
	v_mfma_f32_32x32x16_bf16 v[32:47], v[96:99], v[104:107], v[32:47]
	ds_read_b128 v[96:99], v86 offset:4096
	s_waitcnt vmcnt(0)
	s_waitcnt vmcnt(0) lgkmcnt(0)
	s_barrier
	v_mfma_f32_32x32x16_bf16 v[16:31], v[96:99], v[100:103], v[16:31]
	v_mfma_f32_32x32x16_bf16 v[0:15], v[96:99], v[104:107], v[0:15]
	v_lshl_add_u64 v[96:97], v[64:65], 0, s[56:57]
	global_load_lds_dwordx4 v[96:97], off
	v_lshl_add_u64 v[96:97], v[66:67], 0, s[56:57]
	s_mov_b32 m0, s28
	s_nop 0
	global_load_lds_dwordx4 v[96:97], off
	s_mov_b32 m0, s29
	s_nop 0
	global_load_lds_dwordx4 v[88:89], off
	v_lshl_add_u64 v[88:89], v[70:71], 0, s[56:57]
	s_mov_b32 m0, s40
	s_nop 0
	global_load_lds_dwordx4 v[88:89], off
	v_lshl_add_u64 v[88:89], v[72:73], 0, s[56:57]
	s_mov_b32 m0, s41
	s_nop 0
	global_load_lds_dwordx4 v[88:89], off
	v_lshl_add_u64 v[88:89], v[74:75], 0, s[56:57]
	s_mov_b32 m0, s42
	s_nop 0
	global_load_lds_dwordx4 v[88:89], off
	v_lshl_add_u64 v[88:89], v[76:77], 0, s[56:57]
	s_mov_b32 m0, s43
	s_nop 0
	global_load_lds_dwordx4 v[88:89], off
	v_lshl_add_u64 v[88:89], v[78:79], 0, s[56:57]
	s_mov_b32 m0, s44
	s_nop 0
	global_load_lds_dwordx4 v[88:89], off
	ds_read_b128 v[88:91], v80 offset:32768
	ds_read_b128 v[92:95], v82 offset:49152
	ds_read_b128 v[96:99], v82 offset:53248
	s_waitcnt lgkmcnt(0)
	v_mfma_f32_32x32x16_bf16 v[48:63], v[88:91], v[92:95], v[48:63]
	s_mov_b32 m0, s20
	v_mfma_f32_32x32x16_bf16 v[32:47], v[88:91], v[96:99], v[32:47]
	ds_read_b128 v[88:91], v80 offset:36864
	s_waitcnt lgkmcnt(0)
	v_mfma_f32_32x32x16_bf16 v[16:31], v[88:91], v[92:95], v[16:31]
	v_mfma_f32_32x32x16_bf16 v[0:15], v[88:91], v[96:99], v[0:15]
	ds_read_b128 v[88:91], v81 offset:32768
	ds_read_b128 v[92:95], v83 offset:49152
	ds_read_b128 v[96:99], v83 offset:53248
	s_waitcnt lgkmcnt(0)
	v_mfma_f32_32x32x16_bf16 v[48:63], v[88:91], v[92:95], v[48:63]
	v_mfma_f32_32x32x16_bf16 v[32:47], v[88:91], v[96:99], v[32:47]
	ds_read_b128 v[88:91], v81 offset:36864
	s_waitcnt lgkmcnt(0)
	v_mfma_f32_32x32x16_bf16 v[16:31], v[88:91], v[92:95], v[16:31]
	v_mfma_f32_32x32x16_bf16 v[0:15], v[88:91], v[96:99], v[0:15]
	ds_read_b128 v[88:91], v84 offset:32768
	ds_read_b128 v[92:95], v85 offset:49152
	ds_read_b128 v[96:99], v85 offset:53248
	s_waitcnt lgkmcnt(0)
	v_mfma_f32_32x32x16_bf16 v[48:63], v[88:91], v[92:95], v[48:63]
	v_mfma_f32_32x32x16_bf16 v[32:47], v[88:91], v[96:99], v[32:47]
	ds_read_b128 v[88:91], v84 offset:36864
	s_waitcnt lgkmcnt(0)
	v_mfma_f32_32x32x16_bf16 v[16:31], v[88:91], v[92:95], v[16:31]
	v_mfma_f32_32x32x16_bf16 v[0:15], v[88:91], v[96:99], v[0:15]
	ds_read_b128 v[88:91], v86 offset:32768
	ds_read_b128 v[92:95], v87 offset:49152
	ds_read_b128 v[96:99], v87 offset:53248
	s_waitcnt lgkmcnt(0)
	v_mfma_f32_32x32x16_bf16 v[48:63], v[88:91], v[92:95], v[48:63]
	v_mfma_f32_32x32x16_bf16 v[32:47], v[88:91], v[96:99], v[32:47]
	ds_read_b128 v[88:91], v86 offset:36864
	s_waitcnt vmcnt(0)
	s_waitcnt vmcnt(0) lgkmcnt(0)
	s_barrier
; #define WAIT_V0() asm volatile("s_waitcnt vmcnt(0)" ::: "memory")
; DI void gemm_core(char* smem, int nk, const char* Ab, const char* Bb, const unsigned (&aoff)[4], const unsigned (&boff)[4],
;                   f32x16 (&acc)[2][2]) {
;     ...
;   for (int kt = 0; kt < nk; ++kt) {
;     const int cur = kt & 1;
;     if (kt + 1 < nk) stage(cur ^ 1, kt + 1);
;     const char* sb = smem + cur * STAGE_B;
; #pragma unroll
;     for (int ks = 0; ks < 4; ++ks) {
;       bf16x8 af[2], bfr[2];
; #pragma unroll
;       for (int mb = 0; mb < 2; ++mb) af[mb] = *(const bf16x8*)(sb + a_base + mb * 4096 + xo[ks]);
; #pragma unroll
;       for (int nb = 0; nb < 2; ++nb) bfr[nb] = *(const bf16x8*)(sb + b_base + nb * 4096 + xo[ks]);
; #pragma unroll
;       for (int mb = 0; mb < 2; ++mb)
; #pragma unroll
;         for (int nb = 0; nb < 2; ++nb)
;           acc[mb][nb] = __builtin_amdgcn_mfma_f32_32x32x16_bf16(af[mb], bfr[nb], acc[mb][nb], 0, 0, 0);
;     }
;     WAIT_V0();
;     __syncthreads();
;   }
	v_mfma_f32_32x32x16_bf16 v[16:31], v[88:91], v[92:95], v[16:31]
	v_mfma_f32_32x32x16_bf16 v[0:15], v[88:91], v[96:99], v[0:15]
	v_lshl_add_u64 v[88:89], v[64:65], 0, s[58:59]
	global_load_lds_dwordx4 v[88:89], off
	v_lshl_add_u64 v[88:89], v[66:67], 0, s[58:59]
	s_mov_b32 m0, s21
	s_nop 0
	global_load_lds_dwordx4 v[88:89], off
	v_lshl_add_u64 v[88:89], v[68:69], 0, s[58:59]
	s_mov_b32 m0, s22
	s_nop 0
	global_load_lds_dwordx4 v[88:89], off
	v_lshl_add_u64 v[88:89], v[70:71], 0, s[58:59]
	s_mov_b32 m0, s1
	s_nop 0
	global_load_lds_dwordx4 v[88:89], off
	v_lshl_add_u64 v[88:89], v[72:73], 0, s[58:59]
	s_mov_b32 m0, s16
	s_nop 0
	global_load_lds_dwordx4 v[88:89], off
	v_lshl_add_u64 v[88:89], v[74:75], 0, s[58:59]
	s_mov_b32 m0, s17
	s_nop 0
	global_load_lds_dwordx4 v[88:89], off
	v_lshl_add_u64 v[88:89], v[76:77], 0, s[58:59]
	s_mov_b32 m0, s18
	s_nop 0
	global_load_lds_dwordx4 v[88:89], off
	v_lshl_add_u64 v[88:89], v[78:79], 0, s[58:59]
	s_mov_b32 m0, s19
	s_nop 0
	global_load_lds_dwordx4 v[88:89], off
	ds_read_b128 v[88:91], v80
	ds_read_b128 v[92:95], v82 offset:16384
	ds_read_b128 v[96:99], v82 offset:20480
	s_waitcnt lgkmcnt(0)
	v_mfma_f32_32x32x16_bf16 v[48:63], v[88:91], v[92:95], v[48:63]
	s_mov_b32 m0, s23
	v_mfma_f32_32x32x16_bf16 v[32:47], v[88:91], v[96:99], v[32:47]
	ds_read_b128 v[88:91], v80 offset:4096
	s_waitcnt lgkmcnt(0)
	v_mfma_f32_32x32x16_bf16 v[16:31], v[88:91], v[92:95], v[16:31]
	v_mfma_f32_32x32x16_bf16 v[0:15], v[88:91], v[96:99], v[0:15]
	ds_read_b128 v[88:91], v81
	ds_read_b128 v[92:95], v83 offset:16384
	ds_read_b128 v[96:99], v83 offset:20480
	s_waitcnt lgkmcnt(0)
	v_mfma_f32_32x32x16_bf16 v[48:63], v[88:91], v[92:95], v[48:63]
	v_mfma_f32_32x32x16_bf16 v[32:47], v[88:91], v[96:99], v[32:47]
	ds_read_b128 v[88:91], v81 offset:4096
	s_waitcnt lgkmcnt(0)
	v_mfma_f32_32x32x16_bf16 v[16:31], v[88:91], v[92:95], v[16:31]
	v_mfma_f32_32x32x16_bf16 v[0:15], v[88:91], v[96:99], v[0:15]
	ds_read_b128 v[88:91], v84
	ds_read_b128 v[92:95], v85 offset:16384
	ds_read_b128 v[96:99], v85 offset:20480
	s_waitcnt lgkmcnt(0)
	v_mfma_f32_32x32x16_bf16 v[48:63], v[88:91], v[92:95], v[48:63]
	v_mfma_f32_32x32x16_bf16 v[32:47], v[88:91], v[96:99], v[32:47]
	ds_read_b128 v[88:91], v84 offset:4096
	s_waitcnt lgkmcnt(0)
	v_mfma_f32_32x32x16_bf16 v[16:31], v[88:91], v[92:95], v[16:31]
	v_mfma_f32_32x32x16_bf16 v[0:15], v[88:91], v[96:99], v[0:15]
	ds_read_b128 v[88:91], v86
	ds_read_b128 v[92:95], v87 offset:16384
	ds_read_b128 v[96:99], v87 offset:20480
	s_waitcnt lgkmcnt(0)
	v_mfma_f32_32x32x16_bf16 v[48:63], v[88:91], v[92:95], v[48:63]
	v_mfma_f32_32x32x16_bf16 v[32:47], v[88:91], v[96:99], v[32:47]
	ds_read_b128 v[88:91], v86 offset:4096
	s_waitcnt vmcnt(0)
	s_waitcnt vmcnt(0) lgkmcnt(0)
	s_barrier
	v_mfma_f32_32x32x16_bf16 v[16:31], v[88:91], v[92:95], v[16:31]
	v_mfma_f32_32x32x16_bf16 v[0:15], v[88:91], v[96:99], v[0:15]
	v_lshl_add_u64 v[88:89], v[64:65], 0, s[60:61]
	global_load_lds_dwordx4 v[88:89], off
	v_lshl_add_u64 v[88:89], v[66:67], 0, s[60:61]
	s_mov_b32 m0, s28
	s_nop 0
	global_load_lds_dwordx4 v[88:89], off
	v_lshl_add_u64 v[88:89], v[68:69], 0, s[60:61]
	s_mov_b32 m0, s29
	s_nop 0
	global_load_lds_dwordx4 v[88:89], off
	v_lshl_add_u64 v[88:89], v[70:71], 0, s[60:61]
	s_mov_b32 m0, s40
	s_nop 0
	global_load_lds_dwordx4 v[88:89], off
	v_lshl_add_u64 v[88:89], v[72:73], 0, s[60:61]
	s_mov_b32 m0, s41
	s_nop 0
	global_load_lds_dwordx4 v[88:89], off
	v_lshl_add_u64 v[88:89], v[74:75], 0, s[60:61]
	s_mov_b32 m0, s42
	s_nop 0
	global_load_lds_dwordx4 v[88:89], off
	v_lshl_add_u64 v[88:89], v[76:77], 0, s[60:61]
	s_mov_b32 m0, s43
	s_nop 0
	global_load_lds_dwordx4 v[88:89], off
	v_lshl_add_u64 v[88:89], v[78:79], 0, s[60:61]
	s_mov_b32 m0, s44
	s_nop 0
	global_load_lds_dwordx4 v[88:89], off
	ds_read_b128 v[88:91], v80 offset:32768
	ds_read_b128 v[92:95], v82 offset:49152
	ds_read_b128 v[96:99], v82 offset:53248
	s_waitcnt lgkmcnt(0)
	v_mfma_f32_32x32x16_bf16 v[48:63], v[88:91], v[92:95], v[48:63]
	s_mov_b32 m0, s20
	v_mfma_f32_32x32x16_bf16 v[32:47], v[88:91], v[96:99], v[32:47]
	ds_read_b128 v[88:91], v80 offset:36864
	s_waitcnt lgkmcnt(0)
	v_mfma_f32_32x32x16_bf16 v[16:31], v[88:91], v[92:95], v[16:31]
	v_mfma_f32_32x32x16_bf16 v[0:15], v[88:91], v[96:99], v[0:15]
	ds_read_b128 v[88:91], v81 offset:32768
	ds_read_b128 v[92:95], v83 offset:49152
	ds_read_b128 v[96:99], v83 offset:53248
	s_waitcnt lgkmcnt(0)
	v_mfma_f32_32x32x16_bf16 v[48:63], v[88:91], v[92:95], v[48:63]
	v_mfma_f32_32x32x16_bf16 v[32:47], v[88:91], v[96:99], v[32:47]
	ds_read_b128 v[88:91], v81 offset:36864
	s_waitcnt lgkmcnt(0)
	v_mfma_f32_32x32x16_bf16 v[16:31], v[88:91], v[92:95], v[16:31]
	v_mfma_f32_32x32x16_bf16 v[0:15], v[88:91], v[96:99], v[0:15]
	ds_read_b128 v[88:91], v84 offset:32768
	ds_read_b128 v[92:95], v85 offset:49152
	ds_read_b128 v[96:99], v85 offset:53248
	s_waitcnt lgkmcnt(0)
	v_mfma_f32_32x32x16_bf16 v[48:63], v[88:91], v[92:95], v[48:63]
	v_mfma_f32_32x32x16_bf16 v[32:47], v[88:91], v[96:99], v[32:47]
	ds_read_b128 v[88:91], v84 offset:36864
	s_waitcnt lgkmcnt(0)
	v_mfma_f32_32x32x16_bf16 v[16:31], v[88:91], v[92:95], v[16:31]
	v_mfma_f32_32x32x16_bf16 v[0:15], v[88:91], v[96:99], v[0:15]
	ds_read_b128 v[88:91], v86 offset:32768
	ds_read_b128 v[92:95], v87 offset:49152
	ds_read_b128 v[96:99], v87 offset:53248
	s_waitcnt lgkmcnt(0)
	v_mfma_f32_32x32x16_bf16 v[48:63], v[88:91], v[92:95], v[48:63]
	v_mfma_f32_32x32x16_bf16 v[32:47], v[88:91], v[96:99], v[32:47]
	ds_read_b128 v[88:91], v86 offset:36864
	s_waitcnt vmcnt(0)
	s_waitcnt vmcnt(0) lgkmcnt(0)
	s_barrier
; #define WAIT_V0() asm volatile("s_waitcnt vmcnt(0)" ::: "memory")
; DI void gemm_core(char* smem, int nk, const char* Ab, const char* Bb, const unsigned (&aoff)[4], const unsigned (&boff)[4],
;                   f32x16 (&acc)[2][2]) {
;     ...
;   for (int kt = 0; kt < nk; ++kt) {
;     const int cur = kt & 1;
;     if (kt + 1 < nk) stage(cur ^ 1, kt + 1);
;     const char* sb = smem + cur * STAGE_B;
; #pragma unroll
;     for (int ks = 0; ks < 4; ++ks) {
;       bf16x8 af[2], bfr[2];
; #pragma unroll
;       for (int mb = 0; mb < 2; ++mb) af[mb] = *(const bf16x8*)(sb + a_base + mb * 4096 + xo[ks]);
; #pragma unroll
;       for (int nb = 0; nb < 2; ++nb) bfr[nb] = *(const bf16x8*)(sb + b_base + nb * 4096 + xo[ks]);
; #pragma unroll
;       for (int mb = 0; mb < 2; ++mb)
; #pragma unroll
;         for (int nb = 0; nb < 2; ++nb)
;           acc[mb][nb] = __builtin_amdgcn_mfma_f32_32x32x16_bf16(af[mb], bfr[nb], acc[mb][nb], 0, 0, 0);
;     }
;     WAIT_V0();
;     __syncthreads();
;   }
	v_mfma_f32_32x32x16_bf16 v[16:31], v[88:91], v[92:95], v[16:31]
	v_mfma_f32_32x32x16_bf16 v[0:15], v[88:91], v[96:99], v[0:15]
	v_lshl_add_u64 v[88:89], v[64:65], 0, s[62:63]
	global_load_lds_dwordx4 v[88:89], off
	v_lshl_add_u64 v[88:89], v[66:67], 0, s[62:63]
	s_mov_b32 m0, s21
	s_nop 0
	global_load_lds_dwordx4 v[88:89], off
	v_lshl_add_u64 v[88:89], v[68:69], 0, s[62:63]
	s_mov_b32 m0, s22
	s_nop 0
	global_load_lds_dwordx4 v[88:89], off
	v_lshl_add_u64 v[88:89], v[70:71], 0, s[62:63]
	s_mov_b32 m0, s1
	s_nop 0
	global_load_lds_dwordx4 v[88:89], off
	v_lshl_add_u64 v[88:89], v[72:73], 0, s[62:63]
	s_mov_b32 m0, s16
	s_nop 0
	global_load_lds_dwordx4 v[88:89], off
	v_lshl_add_u64 v[88:89], v[74:75], 0, s[62:63]
	s_mov_b32 m0, s17
	s_nop 0
	global_load_lds_dwordx4 v[88:89], off
	v_lshl_add_u64 v[88:89], v[76:77], 0, s[62:63]
	s_mov_b32 m0, s18
	s_nop 0
	global_load_lds_dwordx4 v[88:89], off
	v_lshl_add_u64 v[88:89], v[78:79], 0, s[62:63]
	s_mov_b32 m0, s19
	s_nop 0
	global_load_lds_dwordx4 v[88:89], off
	ds_read_b128 v[88:91], v80
	ds_read_b128 v[92:95], v82 offset:16384
	ds_read_b128 v[96:99], v82 offset:20480
	s_waitcnt lgkmcnt(0)
	v_mfma_f32_32x32x16_bf16 v[48:63], v[88:91], v[92:95], v[48:63]
	s_mov_b32 m0, s23
	v_mfma_f32_32x32x16_bf16 v[32:47], v[88:91], v[96:99], v[32:47]
	ds_read_b128 v[88:91], v80 offset:4096
	s_waitcnt lgkmcnt(0)
	v_mfma_f32_32x32x16_bf16 v[16:31], v[88:91], v[92:95], v[16:31]
	v_mfma_f32_32x32x16_bf16 v[0:15], v[88:91], v[96:99], v[0:15]
	ds_read_b128 v[88:91], v81
	ds_read_b128 v[92:95], v83 offset:16384
	ds_read_b128 v[96:99], v83 offset:20480
	s_waitcnt lgkmcnt(0)
	v_mfma_f32_32x32x16_bf16 v[48:63], v[88:91], v[92:95], v[48:63]
	v_mfma_f32_32x32x16_bf16 v[32:47], v[88:91], v[96:99], v[32:47]
	ds_read_b128 v[88:91], v81 offset:4096
	s_waitcnt lgkmcnt(0)
	v_mfma_f32_32x32x16_bf16 v[16:31], v[88:91], v[92:95], v[16:31]
	v_mfma_f32_32x32x16_bf16 v[0:15], v[88:91], v[96:99], v[0:15]
	ds_read_b128 v[88:91], v84
	ds_read_b128 v[92:95], v85 offset:16384
	ds_read_b128 v[96:99], v85 offset:20480
	s_waitcnt lgkmcnt(0)
	v_mfma_f32_32x32x16_bf16 v[48:63], v[88:91], v[92:95], v[48:63]
	v_mfma_f32_32x32x16_bf16 v[32:47], v[88:91], v[96:99], v[32:47]
	ds_read_b128 v[88:91], v84 offset:4096
	s_waitcnt lgkmcnt(0)
	v_mfma_f32_32x32x16_bf16 v[16:31], v[88:91], v[92:95], v[16:31]
	v_mfma_f32_32x32x16_bf16 v[0:15], v[88:91], v[96:99], v[0:15]
	ds_read_b128 v[88:91], v86
	ds_read_b128 v[92:95], v87 offset:16384
	ds_read_b128 v[96:99], v87 offset:20480
	s_waitcnt lgkmcnt(0)
	v_mfma_f32_32x32x16_bf16 v[48:63], v[88:91], v[92:95], v[48:63]
	v_mfma_f32_32x32x16_bf16 v[32:47], v[88:91], v[96:99], v[32:47]
	ds_read_b128 v[88:91], v86 offset:4096
	s_waitcnt vmcnt(0)
	s_waitcnt vmcnt(0) lgkmcnt(0)
	s_barrier
	v_mfma_f32_32x32x16_bf16 v[16:31], v[88:91], v[92:95], v[16:31]
	v_mfma_f32_32x32x16_bf16 v[0:15], v[88:91], v[96:99], v[0:15]
	v_lshl_add_u64 v[88:89], v[64:65], 0, s[64:65]
	global_load_lds_dwordx4 v[88:89], off
	v_lshl_add_u64 v[88:89], v[66:67], 0, s[64:65]
	s_mov_b32 m0, s28
	v_lshl_add_u64 v[64:65], v[64:65], 0, s[66:67]
	global_load_lds_dwordx4 v[88:89], off
	v_lshl_add_u64 v[88:89], v[68:69], 0, s[64:65]
	s_mov_b32 m0, s29
	s_nop 0
	global_load_lds_dwordx4 v[88:89], off
	v_lshl_add_u64 v[88:89], v[70:71], 0, s[64:65]
	s_mov_b32 m0, s40
	s_nop 0
	global_load_lds_dwordx4 v[88:89], off
	v_lshl_add_u64 v[88:89], v[72:73], 0, s[64:65]
	s_mov_b32 m0, s41
	s_nop 0
	global_load_lds_dwordx4 v[88:89], off
	v_lshl_add_u64 v[88:89], v[74:75], 0, s[64:65]
	s_mov_b32 m0, s42
	s_nop 0
	global_load_lds_dwordx4 v[88:89], off
	v_lshl_add_u64 v[88:89], v[76:77], 0, s[64:65]
	s_mov_b32 m0, s43
	s_nop 0
	global_load_lds_dwordx4 v[88:89], off
	v_lshl_add_u64 v[88:89], v[78:79], 0, s[64:65]
	s_mov_b32 m0, s44
	s_nop 0
	global_load_lds_dwordx4 v[88:89], off
	ds_read_b128 v[88:91], v80 offset:32768
	ds_read_b128 v[92:95], v82 offset:49152
	ds_read_b128 v[96:99], v82 offset:53248
	s_waitcnt lgkmcnt(0)
	v_mfma_f32_32x32x16_bf16 v[48:63], v[88:91], v[92:95], v[48:63]
	s_mov_b32 m0, s20
	v_mfma_f32_32x32x16_bf16 v[32:47], v[88:91], v[96:99], v[32:47]
	ds_read_b128 v[88:91], v80 offset:36864
	s_waitcnt lgkmcnt(0)
	v_mfma_f32_32x32x16_bf16 v[16:31], v[88:91], v[92:95], v[16:31]
	v_mfma_f32_32x32x16_bf16 v[0:15], v[88:91], v[96:99], v[0:15]
	ds_read_b128 v[88:91], v81 offset:32768
	ds_read_b128 v[92:95], v83 offset:49152
	ds_read_b128 v[96:99], v83 offset:53248
	s_waitcnt lgkmcnt(0)
	v_mfma_f32_32x32x16_bf16 v[48:63], v[88:91], v[92:95], v[48:63]
	v_mfma_f32_32x32x16_bf16 v[32:47], v[88:91], v[96:99], v[32:47]
	ds_read_b128 v[88:91], v81 offset:36864
	s_waitcnt lgkmcnt(0)
	v_mfma_f32_32x32x16_bf16 v[16:31], v[88:91], v[92:95], v[16:31]
	v_mfma_f32_32x32x16_bf16 v[0:15], v[88:91], v[96:99], v[0:15]
	ds_read_b128 v[88:91], v84 offset:32768
	ds_read_b128 v[92:95], v85 offset:49152
	ds_read_b128 v[96:99], v85 offset:53248
	s_waitcnt lgkmcnt(0)
	v_mfma_f32_32x32x16_bf16 v[48:63], v[88:91], v[92:95], v[48:63]
	v_mfma_f32_32x32x16_bf16 v[32:47], v[88:91], v[96:99], v[32:47]
	ds_read_b128 v[88:91], v84 offset:36864
	s_waitcnt lgkmcnt(0)
	v_mfma_f32_32x32x16_bf16 v[16:31], v[88:91], v[92:95], v[16:31]
	v_mfma_f32_32x32x16_bf16 v[0:15], v[88:91], v[96:99], v[0:15]
	ds_read_b128 v[88:91], v86 offset:32768
	ds_read_b128 v[92:95], v87 offset:49152
	ds_read_b128 v[96:99], v87 offset:53248
	s_waitcnt lgkmcnt(0)
	v_mfma_f32_32x32x16_bf16 v[48:63], v[88:91], v[92:95], v[48:63]
	v_mfma_f32_32x32x16_bf16 v[32:47], v[88:91], v[96:99], v[32:47]
	ds_read_b128 v[88:91], v86 offset:36864
	s_waitcnt vmcnt(0)
	s_waitcnt vmcnt(0) lgkmcnt(0)
	s_barrier
; #define WAIT_V0() asm volatile("s_waitcnt vmcnt(0)" ::: "memory")
; DI void gemm_core(char* smem, int nk, const char* Ab, const char* Bb, const unsigned (&aoff)[4], const unsigned (&boff)[4],
;                   f32x16 (&acc)[2][2]) {
;     ...
;   for (int kt = 0; kt < nk; ++kt) {
;     const int cur = kt & 1;
;     if (kt + 1 < nk) stage(cur ^ 1, kt + 1);
;     const char* sb = smem + cur * STAGE_B;
; #pragma unroll
;     for (int ks = 0; ks < 4; ++ks) {
;       bf16x8 af[2], bfr[2];
; #pragma unroll
;       for (int mb = 0; mb < 2; ++mb) af[mb] = *(const bf16x8*)(sb + a_base + mb * 4096 + xo[ks]);
; #pragma unroll
;       for (int nb = 0; nb < 2; ++nb) bfr[nb] = *(const bf16x8*)(sb + b_base + nb * 4096 + xo[ks]);
; #pragma unroll
;       for (int mb = 0; mb < 2; ++mb)
; #pragma unroll
;         for (int nb = 0; nb < 2; ++nb)
;           acc[mb][nb] = __builtin_amdgcn_mfma_f32_32x32x16_bf16(af[mb], bfr[nb], acc[mb][nb], 0, 0, 0);
;     }
;     WAIT_V0();
;     __syncthreads();
;   }
; DI void phase_gemm_in(const Params& P, int layer, char* smem) {
;     ...
;     epi_foreach(acc, [&](int row, int col, float v) __attribute__((always_inline)) {
;       const int c = n0 + col;
;       Cs[row * 136 + col] = (c >= C_QI && c < C_CQ) ? f2h(v) : f2bf(v);
;     });
	global_load_lds_dwordx4 v[64:65], off
	v_lshl_add_u64 v[64:65], v[66:67], 0, s[66:67]
	s_mov_b32 m0, s21
	v_mfma_f32_32x32x16_bf16 v[16:31], v[88:91], v[92:95], v[16:31]
	global_load_lds_dwordx4 v[64:65], off
	v_lshl_add_u64 v[64:65], v[68:69], 0, s[66:67]
	s_mov_b32 m0, s22
	s_nop 0
	global_load_lds_dwordx4 v[64:65], off
	v_lshl_add_u64 v[64:65], v[70:71], 0, s[66:67]
	s_mov_b32 m0, s1
	v_mfma_f32_32x32x16_bf16 v[0:15], v[88:91], v[96:99], v[0:15]
	global_load_lds_dwordx4 v[64:65], off
	v_lshl_add_u64 v[64:65], v[72:73], 0, s[66:67]
	s_mov_b32 m0, s16
	v_mov_b32_e32 v96, v161
	global_load_lds_dwordx4 v[64:65], off
	v_lshl_add_u64 v[64:65], v[74:75], 0, s[66:67]
	s_mov_b32 m0, s17
	v_mov_b32_e32 v97, v161
	global_load_lds_dwordx4 v[64:65], off
	v_lshl_add_u64 v[64:65], v[76:77], 0, s[66:67]
	s_mov_b32 m0, s18
	s_add_i32 s1, s10, 0xfffffa00
	global_load_lds_dwordx4 v[64:65], off
	v_lshl_add_u64 v[64:65], v[78:79], 0, s[66:67]
	s_mov_b32 m0, s19
	s_nop 0
	global_load_lds_dwordx4 v[64:65], off
	ds_read_b128 v[64:67], v80
	ds_read_b128 v[68:71], v82 offset:16384
	ds_read_b128 v[72:75], v82 offset:20480
	s_waitcnt lgkmcnt(0)
	v_mfma_f32_32x32x16_bf16 v[48:63], v[64:67], v[68:71], v[48:63]
	v_mfma_f32_32x32x16_bf16 v[32:47], v[64:67], v[72:75], v[32:47]
	ds_read_b128 v[64:67], v80 offset:4096
	s_waitcnt lgkmcnt(0)
	v_mfma_f32_32x32x16_bf16 v[16:31], v[64:67], v[68:71], v[16:31]
	v_mfma_f32_32x32x16_bf16 v[0:15], v[64:67], v[72:75], v[0:15]
	ds_read_b128 v[64:67], v81
	ds_read_b128 v[68:71], v83 offset:16384
	ds_read_b128 v[72:75], v83 offset:20480
	s_waitcnt lgkmcnt(0)
	v_mfma_f32_32x32x16_bf16 v[48:63], v[64:67], v[68:71], v[48:63]
	v_mfma_f32_32x32x16_bf16 v[32:47], v[64:67], v[72:75], v[32:47]
	ds_read_b128 v[64:67], v81 offset:4096
	s_waitcnt lgkmcnt(0)
	v_mfma_f32_32x32x16_bf16 v[16:31], v[64:67], v[68:71], v[16:31]
	v_mfma_f32_32x32x16_bf16 v[0:15], v[64:67], v[72:75], v[0:15]
	ds_read_b128 v[64:67], v84
	ds_read_b128 v[68:71], v85 offset:16384
	ds_read_b128 v[72:75], v85 offset:20480
	s_waitcnt lgkmcnt(0)
	v_mfma_f32_32x32x16_bf16 v[48:63], v[64:67], v[68:71], v[48:63]
	v_mfma_f32_32x32x16_bf16 v[32:47], v[64:67], v[72:75], v[32:47]
	ds_read_b128 v[64:67], v84 offset:4096
	s_waitcnt lgkmcnt(0)
	v_mfma_f32_32x32x16_bf16 v[16:31], v[64:67], v[68:71], v[16:31]
	v_mfma_f32_32x32x16_bf16 v[0:15], v[64:67], v[72:75], v[0:15]
	ds_read_b128 v[64:67], v86
	ds_read_b128 v[68:71], v87 offset:16384
	ds_read_b128 v[72:75], v87 offset:20480
	s_waitcnt lgkmcnt(0)
	v_mfma_f32_32x32x16_bf16 v[48:63], v[64:67], v[68:71], v[48:63]
	v_mfma_f32_32x32x16_bf16 v[32:47], v[64:67], v[72:75], v[32:47]
	ds_read_b128 v[64:67], v86 offset:4096
	s_waitcnt vmcnt(0)
	s_waitcnt vmcnt(0) lgkmcnt(0)
	s_barrier
	v_mfma_f32_32x32x16_bf16 v[16:31], v[64:67], v[68:71], v[16:31]
	v_mfma_f32_32x32x16_bf16 v[0:15], v[64:67], v[72:75], v[0:15]
	ds_read_b128 v[64:67], v80 offset:32768
	ds_read_b128 v[68:71], v82 offset:49152
	ds_read_b128 v[72:75], v82 offset:53248
	s_waitcnt lgkmcnt(1)
	v_mfma_f32_32x32x16_bf16 v[48:63], v[64:67], v[68:71], v[48:63]
	s_waitcnt lgkmcnt(0)
	v_mfma_f32_32x32x16_bf16 v[32:47], v[64:67], v[72:75], v[32:47]
	ds_read_b128 v[64:67], v80 offset:36864
	s_waitcnt lgkmcnt(0)
	v_mfma_f32_32x32x16_bf16 v[16:31], v[64:67], v[68:71], v[16:31]
	v_mfma_f32_32x32x16_bf16 v[0:15], v[64:67], v[72:75], v[0:15]
	ds_read_b128 v[64:67], v81 offset:32768
	ds_read_b128 v[68:71], v83 offset:49152
	ds_read_b128 v[72:75], v83 offset:53248
	s_waitcnt lgkmcnt(1)
	v_mfma_f32_32x32x16_bf16 v[48:63], v[64:67], v[68:71], v[48:63]
	s_waitcnt lgkmcnt(0)
	v_mfma_f32_32x32x16_bf16 v[32:47], v[64:67], v[72:75], v[32:47]
	ds_read_b128 v[64:67], v81 offset:36864
	s_waitcnt lgkmcnt(0)
	v_mfma_f32_32x32x16_bf16 v[16:31], v[64:67], v[68:71], v[16:31]
	ds_read_b128 v[68:71], v84 offset:32768
	ds_read_b128 v[76:79], v84 offset:36864
	v_mfma_f32_32x32x16_bf16 v[0:15], v[64:67], v[72:75], v[0:15]
	ds_read_b128 v[64:67], v85 offset:49152
	ds_read_b128 v[72:75], v85 offset:53248
	ds_read_b128 v[80:83], v86 offset:32768
	ds_read_b128 v[88:91], v86 offset:36864
	ds_read_b128 v[92:95], v87 offset:49152
	ds_read_b128 v[84:87], v87 offset:53248
	s_waitcnt vmcnt(0)
	s_waitcnt lgkmcnt(0)
	s_barrier
	v_mfma_f32_32x32x16_bf16 v[48:63], v[68:71], v[64:67], v[48:63]
	v_mfma_f32_32x32x16_bf16 v[48:63], v[80:83], v[92:95], v[48:63]
	v_mfma_f32_32x32x16_bf16 v[32:47], v[68:71], v[72:75], v[32:47]
	v_lshrrev_b32_e32 v69, 3, v96
	v_lshrrev_b32_e32 v68, 1, v97
	v_and_b32_e32 v69, 4, v69
	v_and_b32_e32 v70, 31, v96
	v_and_or_b32 v68, v68, s7, v69
	s_nop 5
	v_cvt_f16_f32_e32 v69, v48
	v_and_or_b32 v70, v97, 64, v70
	v_or_b32_e32 v71, s1, v70
	v_cmp_gt_u32_e64 s[40:41], s45, v71
	v_cvt_pk_bf16_f32 v48, v48, s0
	v_mfma_f32_32x32x16_bf16 v[16:31], v[76:79], v[64:67], v[16:31]
	v_cndmask_b32_e64 v69, v48, v69, s[40:41]
	v_mul_lo_u32 v48, v68, s97
	v_cvt_f16_f32_e32 v68, v49
	v_cvt_pk_bf16_f32 v49, v49, s0
	v_lshl_add_u32 v48, v70, 1, v48
	v_cvt_f16_f32_e32 v64, v51
	v_cndmask_b32_e64 v49, v49, v68, s[40:41]
	ds_write_b16 v48, v49 offset:272
	v_cvt_f16_f32_e32 v49, v50
	v_cvt_pk_bf16_f32 v50, v50, s0
	v_mfma_f32_32x32x16_bf16 v[0:15], v[76:79], v[72:75], v[0:15]
	ds_write_b16 v48, v69
	v_cndmask_b32_e64 v49, v50, v49, s[40:41]
	ds_write_b16 v48, v49 offset:544
	v_cvt_pk_bf16_f32 v49, v51, s0
	v_cndmask_b32_e64 v49, v49, v64, s[40:41]
	ds_write_b16 v48, v49 offset:816
	v_cvt_f16_f32_e32 v49, v52
	v_cvt_f16_f32_e32 v51, v53
	v_cvt_pk_bf16_f32 v50, v52, s0
	v_mfma_f32_32x32x16_bf16 v[32:47], v[80:83], v[84:87], v[32:47]
	v_cndmask_b32_e64 v49, v50, v49, s[40:41]
	v_cvt_f16_f32_e32 v50, v54
	ds_write_b16 v48, v49 offset:2176
; DI int ltid() { int t = threadIdx.x; asm volatile("" : "+v"(t)); return t; }
; template <class F>
; DI void epi_foreach(const f32x16 (&acc)[2][2], F f) {
;   const int lane = ltid() & 63, w = ltid() >> 6;
;   const int wm = w >> 1, wn = w & 1;
; #pragma unroll
;   for (int mb = 0; mb < 2; ++mb)
; #pragma unroll
;     for (int nb = 0; nb < 2; ++nb)
; #pragma unroll
;       for (int r = 0; r < 16; ++r) {
;         const int row = wm * 64 + mb * 32 + (r & 3) + 8 * (r >> 2) + 4 * (lane >> 5);
;         const int col = wn * 64 + nb * 32 + (lane & 31);
;         f(row, col, acc[mb][nb][r]);
;         if ((r & 7) == 7) __builtin_amdgcn_sched_barrier(0);
;       }
; }
; DI void phase_gemm_in(const Params& P, int layer, char* smem) {
;     ...
;     epi_foreach(acc, [&](int row, int col, float v) __attribute__((always_inline)) {
;       const int c = n0 + col;
;       Cs[row * 136 + col] = (c >= C_QI && c < C_CQ) ? f2h(v) : f2bf(v);
;     });
	v_cvt_pk_bf16_f32 v49, v53, s0
	v_cndmask_b32_e64 v49, v49, v51, s[40:41]
	v_cvt_f16_f32_e32 v51, v55
	ds_write_b16 v48, v49 offset:2448
	v_cvt_pk_bf16_f32 v49, v54, s0
	v_cndmask_b32_e64 v49, v49, v50, s[40:41]
	ds_write_b16 v48, v49 offset:2720
	v_cvt_pk_bf16_f32 v49, v55, s0
	v_cndmask_b32_e64 v49, v49, v51, s[40:41]
	v_mfma_f32_32x32x16_bf16 v[16:31], v[88:91], v[92:95], v[16:31]
	ds_write_b16 v48, v49 offset:2992
	v_mfma_f32_32x32x16_bf16 v[0:15], v[88:91], v[84:87], v[0:15]
	v_cvt_f16_f32_e32 v49, v56
	v_cvt_pk_bf16_f32 v50, v56, s0
	v_cndmask_b32_e64 v49, v50, v49, s[40:41]
	ds_write_b16 v48, v49 offset:4352
	v_cvt_f16_f32_e32 v49, v57
	v_cvt_pk_bf16_f32 v50, v57, s0
	v_cndmask_b32_e64 v49, v50, v49, s[40:41]
	ds_write_b16 v48, v49 offset:4624
	v_cvt_f16_f32_e32 v49, v58
	v_cvt_pk_bf16_f32 v50, v58, s0
	v_cndmask_b32_e64 v49, v50, v49, s[40:41]
	ds_write_b16 v48, v49 offset:4896
	v_cvt_f16_f32_e32 v49, v59
	v_cvt_pk_bf16_f32 v50, v59, s0
	v_cndmask_b32_e64 v49, v50, v49, s[40:41]
	ds_write_b16 v48, v49 offset:5168
	v_cvt_f16_f32_e32 v49, v60
	v_cvt_pk_bf16_f32 v50, v60, s0
	v_cndmask_b32_e64 v49, v50, v49, s[40:41]
	ds_write_b16 v48, v49 offset:6528
	v_cvt_f16_f32_e32 v49, v61
	v_cvt_pk_bf16_f32 v50, v61, s0
	v_cndmask_b32_e64 v49, v50, v49, s[40:41]
	ds_write_b16 v48, v49 offset:6800
	v_cvt_f16_f32_e32 v49, v62
	v_cvt_pk_bf16_f32 v50, v62, s0
	v_cndmask_b32_e64 v49, v50, v49, s[40:41]
	ds_write_b16 v48, v49 offset:7072
	v_cvt_f16_f32_e32 v49, v63
	v_cvt_pk_bf16_f32 v50, v63, s0
	v_cndmask_b32_e64 v49, v50, v49, s[40:41]
	ds_write_b16 v48, v49 offset:7344
	s_add_i32 s1, s10, 0xfffffa20
	v_or_b32_e32 v49, s1, v70
	v_cmp_gt_u32_e32 vcc, s45, v49
	v_cvt_f16_f32_e32 v49, v32
	v_cvt_pk_bf16_f32 v32, v32, s0
	v_cndmask_b32_e32 v32, v32, v49, vcc
	ds_write_b16 v48, v32 offset:64
	v_cvt_f16_f32_e32 v32, v33
	v_cvt_pk_bf16_f32 v33, v33, s0
	v_cndmask_b32_e32 v32, v33, v32, vcc
	ds_write_b16 v48, v32 offset:336
	v_cvt_f16_f32_e32 v32, v34
	v_cvt_pk_bf16_f32 v33, v34, s0
	v_cndmask_b32_e32 v32, v33, v32, vcc
	ds_write_b16 v48, v32 offset:608
	v_cvt_f16_f32_e32 v32, v35
	v_cvt_pk_bf16_f32 v33, v35, s0
	v_cndmask_b32_e32 v32, v33, v32, vcc
	ds_write_b16 v48, v32 offset:880
	v_cvt_f16_f32_e32 v32, v36
	v_cvt_pk_bf16_f32 v33, v36, s0
	v_cndmask_b32_e32 v32, v33, v32, vcc
	ds_write_b16 v48, v32 offset:2240
	v_cvt_f16_f32_e32 v32, v37
	v_cvt_pk_bf16_f32 v33, v37, s0
	v_cndmask_b32_e32 v32, v33, v32, vcc
	ds_write_b16 v48, v32 offset:2512
	v_cvt_f16_f32_e32 v32, v38
	v_cvt_pk_bf16_f32 v33, v38, s0
	v_cndmask_b32_e32 v32, v33, v32, vcc
	ds_write_b16 v48, v32 offset:2784
	v_cvt_f16_f32_e32 v32, v39
	v_cvt_pk_bf16_f32 v33, v39, s0
	v_cndmask_b32_e32 v32, v33, v32, vcc
	ds_write_b16 v48, v32 offset:3056
	v_cvt_f16_f32_e32 v32, v40
	v_cvt_pk_bf16_f32 v33, v40, s0
	v_cndmask_b32_e32 v32, v33, v32, vcc
	ds_write_b16 v48, v32 offset:4416
	v_cvt_f16_f32_e32 v32, v41
	v_cvt_pk_bf16_f32 v33, v41, s0
	v_cndmask_b32_e32 v32, v33, v32, vcc
	ds_write_b16 v48, v32 offset:4688
	v_cvt_f16_f32_e32 v32, v42
	v_cvt_pk_bf16_f32 v33, v42, s0
	v_cndmask_b32_e32 v32, v33, v32, vcc
	ds_write_b16 v48, v32 offset:4960
	v_cvt_f16_f32_e32 v32, v43
	v_cvt_pk_bf16_f32 v33, v43, s0
	v_cndmask_b32_e32 v32, v33, v32, vcc
	ds_write_b16 v48, v32 offset:5232
	v_cvt_f16_f32_e32 v32, v44
	v_cvt_pk_bf16_f32 v33, v44, s0
	v_cndmask_b32_e32 v32, v33, v32, vcc
	ds_write_b16 v48, v32 offset:6592
	v_cvt_f16_f32_e32 v32, v45
	v_cvt_pk_bf16_f32 v33, v45, s0
	v_cndmask_b32_e32 v32, v33, v32, vcc
	ds_write_b16 v48, v32 offset:6864
	v_cvt_f16_f32_e32 v32, v46
	v_cvt_pk_bf16_f32 v33, v46, s0
	v_cndmask_b32_e32 v32, v33, v32, vcc
	ds_write_b16 v48, v32 offset:7136
	v_cvt_f16_f32_e32 v32, v47
	v_cvt_pk_bf16_f32 v33, v47, s0
	v_cndmask_b32_e32 v32, v33, v32, vcc
	ds_write_b16 v48, v32 offset:7408
	v_cvt_f16_f32_e32 v32, v16
	v_cvt_pk_bf16_f32 v16, v16, s0
	v_cndmask_b32_e64 v16, v16, v32, s[40:41]
	ds_write_b16 v48, v16 offset:8704
	v_cvt_f16_f32_e32 v16, v17
	v_cvt_pk_bf16_f32 v17, v17, s0
	v_cndmask_b32_e64 v16, v17, v16, s[40:41]
	ds_write_b16 v48, v16 offset:8976
	v_cvt_f16_f32_e32 v16, v18
	v_cvt_pk_bf16_f32 v17, v18, s0
	v_cndmask_b32_e64 v16, v17, v16, s[40:41]
	ds_write_b16 v48, v16 offset:9248
	v_cvt_f16_f32_e32 v16, v19
	v_cvt_pk_bf16_f32 v17, v19, s0
	v_cndmask_b32_e64 v16, v17, v16, s[40:41]
	ds_write_b16 v48, v16 offset:9520
	v_cvt_f16_f32_e32 v16, v20
	v_cvt_pk_bf16_f32 v17, v20, s0
	v_cndmask_b32_e64 v16, v17, v16, s[40:41]
	ds_write_b16 v48, v16 offset:10880
	v_cvt_f16_f32_e32 v16, v21
	v_cvt_pk_bf16_f32 v17, v21, s0
	v_cndmask_b32_e64 v16, v17, v16, s[40:41]
	ds_write_b16 v48, v16 offset:11152
	v_cvt_f16_f32_e32 v16, v22
	v_cvt_pk_bf16_f32 v17, v22, s0
	v_cndmask_b32_e64 v16, v17, v16, s[40:41]
	ds_write_b16 v48, v16 offset:11424
	v_cvt_f16_f32_e32 v16, v23
	v_cvt_pk_bf16_f32 v17, v23, s0
	v_cndmask_b32_e64 v16, v17, v16, s[40:41]
	ds_write_b16 v48, v16 offset:11696
	v_cvt_f16_f32_e32 v16, v24
	v_cvt_pk_bf16_f32 v17, v24, s0
	v_cndmask_b32_e64 v16, v17, v16, s[40:41]
	ds_write_b16 v48, v16 offset:13056
	v_cvt_f16_f32_e32 v16, v25
	v_cvt_pk_bf16_f32 v17, v25, s0
	v_cndmask_b32_e64 v16, v17, v16, s[40:41]
	ds_write_b16 v48, v16 offset:13328
	v_cvt_f16_f32_e32 v16, v26
	v_cvt_pk_bf16_f32 v17, v26, s0
; DI int ltid() { int t = threadIdx.x; asm volatile("" : "+v"(t)); return t; }
; DI void store_tile16(const unsigned short* Cs, unsigned short* dst, int ldd) {
;   const int tid = ltid();
; #pragma unroll
;   for (int i = 0; i < 8; ++i) {
;     const int idx = tid + 256 * i;
;     const int row = idx >> 4, c8 = (idx & 15) * 8;
;     *(u32x4*)(dst + (size_t)row * ldd + c8) = *(const u32x4*)(Cs + row * 136 + c8);
;   }
; }
; DI void phase_gemm_in(const Params& P, int layer, char* smem) {
;     ...
;     epi_foreach(acc, [&](int row, int col, float v) __attribute__((always_inline)) {
;       const int c = n0 + col;
;       Cs[row * 136 + col] = (c >= C_QI && c < C_CQ) ? f2h(v) : f2bf(v);
;     });
;     __syncthreads();
;     store_tile16(Cs, Z + (size_t)m0 * ZLD + n0, ZLD);
;     __syncthreads();
	v_cndmask_b32_e64 v16, v17, v16, s[40:41]
	ds_write_b16 v48, v16 offset:13600
	v_cvt_f16_f32_e32 v16, v27
	v_cvt_pk_bf16_f32 v17, v27, s0
	v_cndmask_b32_e64 v16, v17, v16, s[40:41]
	ds_write_b16 v48, v16 offset:13872
	v_cvt_f16_f32_e32 v16, v28
	v_cvt_pk_bf16_f32 v17, v28, s0
	v_cndmask_b32_e64 v16, v17, v16, s[40:41]
	ds_write_b16 v48, v16 offset:15232
	v_cvt_f16_f32_e32 v16, v29
	v_cvt_pk_bf16_f32 v17, v29, s0
	v_cndmask_b32_e64 v16, v17, v16, s[40:41]
	ds_write_b16 v48, v16 offset:15504
	v_cvt_f16_f32_e32 v16, v30
	v_cvt_pk_bf16_f32 v17, v30, s0
	v_cndmask_b32_e64 v16, v17, v16, s[40:41]
	ds_write_b16 v48, v16 offset:15776
	v_cvt_f16_f32_e32 v16, v31
	v_cvt_pk_bf16_f32 v17, v31, s0
	v_cndmask_b32_e64 v16, v17, v16, s[40:41]
	ds_write_b16 v48, v16 offset:16048
	v_cvt_f16_f32_e32 v16, v0
	v_cvt_pk_bf16_f32 v0, v0, s0
	v_cndmask_b32_e32 v0, v0, v16, vcc
	ds_write_b16 v48, v0 offset:8768
	v_cvt_f16_f32_e32 v0, v1
	v_cvt_pk_bf16_f32 v1, v1, s0
	v_cndmask_b32_e32 v0, v1, v0, vcc
	ds_write_b16 v48, v0 offset:9040
	v_cvt_f16_f32_e32 v0, v2
	v_cvt_pk_bf16_f32 v1, v2, s0
	v_cndmask_b32_e32 v0, v1, v0, vcc
	ds_write_b16 v48, v0 offset:9312
	v_cvt_f16_f32_e32 v0, v3
	v_cvt_pk_bf16_f32 v1, v3, s0
	v_cndmask_b32_e32 v0, v1, v0, vcc
	ds_write_b16 v48, v0 offset:9584
	v_cvt_f16_f32_e32 v0, v4
	v_cvt_pk_bf16_f32 v1, v4, s0
	v_cndmask_b32_e32 v0, v1, v0, vcc
	ds_write_b16 v48, v0 offset:10944
	v_cvt_f16_f32_e32 v0, v5
	v_cvt_pk_bf16_f32 v1, v5, s0
	v_cndmask_b32_e32 v0, v1, v0, vcc
	ds_write_b16 v48, v0 offset:11216
	v_cvt_f16_f32_e32 v0, v6
	v_cvt_pk_bf16_f32 v1, v6, s0
	v_cndmask_b32_e32 v0, v1, v0, vcc
	ds_write_b16 v48, v0 offset:11488
	v_cvt_f16_f32_e32 v0, v7
	v_cvt_pk_bf16_f32 v1, v7, s0
	v_cndmask_b32_e32 v0, v1, v0, vcc
	ds_write_b16 v48, v0 offset:11760
	v_cvt_f16_f32_e32 v0, v8
	v_cvt_pk_bf16_f32 v1, v8, s0
	v_cndmask_b32_e32 v0, v1, v0, vcc
	ds_write_b16 v48, v0 offset:13120
	v_cvt_f16_f32_e32 v0, v9
	v_cvt_pk_bf16_f32 v1, v9, s0
	v_cndmask_b32_e32 v0, v1, v0, vcc
	ds_write_b16 v48, v0 offset:13392
	v_cvt_f16_f32_e32 v0, v10
	v_cvt_pk_bf16_f32 v1, v10, s0
	v_cndmask_b32_e32 v0, v1, v0, vcc
	ds_write_b16 v48, v0 offset:13664
	v_cvt_f16_f32_e32 v0, v11
	v_cvt_pk_bf16_f32 v1, v11, s0
	v_cndmask_b32_e32 v0, v1, v0, vcc
	ds_write_b16 v48, v0 offset:13936
	v_cvt_f16_f32_e32 v0, v12
	v_cvt_pk_bf16_f32 v1, v12, s0
	v_cndmask_b32_e32 v0, v1, v0, vcc
	ds_write_b16 v48, v0 offset:15296
	v_cvt_f16_f32_e32 v0, v13
	v_cvt_pk_bf16_f32 v1, v13, s0
	v_cndmask_b32_e32 v0, v1, v0, vcc
	ds_write_b16 v48, v0 offset:15568
	v_cvt_f16_f32_e32 v0, v14
	v_cvt_pk_bf16_f32 v1, v14, s0
	v_cndmask_b32_e32 v0, v1, v0, vcc
	ds_write_b16 v48, v0 offset:15840
	v_cvt_f16_f32_e32 v0, v15
	v_cvt_pk_bf16_f32 v1, v15, s0
	v_cndmask_b32_e32 v0, v1, v0, vcc
	ds_write_b16 v48, v0 offset:16112
	s_mul_i32 s15, s15, 0xb0000
	s_mul_hi_i32 s0, s0, 0x1600
	s_add_u32 s15, s86, s15
	s_addc_u32 s16, s87, s0
	s_lshl_b64 s[0:1], s[10:11], 1
	v_mov_b32_e32 v8, v161
	s_waitcnt lgkmcnt(0)
	s_barrier
	s_add_u32 s0, s15, s0
	s_addc_u32 s1, s16, s1
	v_lshlrev_b32_e32 v0, 4, v8
	v_and_b32_e32 v136, 0xf0, v0
	v_ashrrev_i32_e32 v6, 4, v8
	v_lshl_add_u64 v[4:5], s[0:1], 0, v[136:137]
	v_mad_u64_u32 v[0:1], s[0:1], v6, s97, v[136:137]
	ds_read_b128 v[0:3], v0
	v_mad_i64_i32 v[6:7], s[0:1], v6, s33, v[4:5]
	s_add_i32 s14, s14, s70
	s_add_i32 s13, s13, s3
	s_waitcnt lgkmcnt(0)
	global_store_dwordx4 v[6:7], v[0:3], off sc1
	s_cmpk_gt_i32 s14, 0x15ff
	s_nop 0
	v_add_u32_e32 v0, 0x100, v8
	v_ashrrev_i32_e32 v6, 4, v0
	v_mad_u64_u32 v[0:1], s[0:1], v6, s97, v[136:137]
	ds_read_b128 v[0:3], v0
	v_mad_i64_i32 v[6:7], s[0:1], v6, s33, v[4:5]
	s_waitcnt lgkmcnt(0)
	global_store_dwordx4 v[6:7], v[0:3], off sc1
	s_nop 1
	v_add_u32_e32 v0, 0x200, v8
	v_ashrrev_i32_e32 v6, 4, v0
	v_mad_u64_u32 v[0:1], s[0:1], v6, s97, v[136:137]
	ds_read_b128 v[0:3], v0
	v_mad_i64_i32 v[6:7], s[0:1], v6, s33, v[4:5]
	s_waitcnt lgkmcnt(0)
	global_store_dwordx4 v[6:7], v[0:3], off sc1
	s_nop 1
	v_add_u32_e32 v0, 0x300, v8
	v_ashrrev_i32_e32 v6, 4, v0
	v_mad_u64_u32 v[0:1], s[0:1], v6, s97, v[136:137]
	ds_read_b128 v[0:3], v0
	v_mad_i64_i32 v[6:7], s[0:1], v6, s33, v[4:5]
	s_waitcnt lgkmcnt(0)
	global_store_dwordx4 v[6:7], v[0:3], off sc1
	s_nop 1
	v_add_u32_e32 v0, 0x400, v8
	v_ashrrev_i32_e32 v6, 4, v0
	v_mad_u64_u32 v[0:1], s[0:1], v6, s97, v[136:137]
	ds_read_b128 v[0:3], v0
	v_mad_i64_i32 v[6:7], s[0:1], v6, s33, v[4:5]
	s_waitcnt lgkmcnt(0)
	global_store_dwordx4 v[6:7], v[0:3], off sc1
	s_nop 1
	v_add_u32_e32 v0, 0x500, v8
	v_ashrrev_i32_e32 v6, 4, v0
	v_mad_u64_u32 v[0:1], s[0:1], v6, s97, v[136:137]
	ds_read_b128 v[0:3], v0
	v_mad_i64_i32 v[6:7], s[0:1], v6, s33, v[4:5]
	s_waitcnt lgkmcnt(0)
	global_store_dwordx4 v[6:7], v[0:3], off sc1
	s_nop 1
	v_add_u32_e32 v0, 0x600, v8
	v_ashrrev_i32_e32 v6, 4, v0
	v_mad_u64_u32 v[0:1], s[0:1], v6, s97, v[136:137]
	ds_read_b128 v[0:3], v0
	v_mad_i64_i32 v[6:7], s[0:1], v6, s33, v[4:5]
	s_waitcnt lgkmcnt(0)
	global_store_dwordx4 v[6:7], v[0:3], off sc1
	s_nop 1
	v_add_u32_e32 v0, 0x700, v8
	v_ashrrev_i32_e32 v6, 4, v0
	v_mad_u64_u32 v[0:1], s[0:1], v6, s97, v[136:137]
	ds_read_b128 v[0:3], v0
	v_mad_i64_i32 v[4:5], s[0:1], v6, s33, v[4:5]
	s_waitcnt lgkmcnt(0)
	global_store_dwordx4 v[4:5], v[0:3], off sc1
	s_barrier
	s_cbranch_scc0 .LBB0_436
